# hand-written layer-1 pooling prep phase (batched loads, per-wave rstd table in LDS, no serialized per-row waits)
# speedup vs baseline: 1.0177x; 1.0177x over previous
.LBB0_460:
	s_andn2_b64 vcc, exec, s[0:1]
	s_cbranch_vccnz .LBB0_996
	s_cmp_gt_i32 s54, 0
	s_mov_b64 s[0:1], -1
	s_cbranch_scc0 .LBB0_723
	s_waitcnt vmcnt(0) lgkmcnt(0)
	s_load_dwordx2 s[4:5], s[78:79], 0xa0
	s_load_dwordx2 s[6:7], s[78:79], 0x28
	s_load_dwordx2 s[8:9], s[78:79], 0x98
	s_load_dwordx2 s[10:11], s[78:79], 0x10
	v_and_b32_e32 v28, 63, v170
	v_lshrrev_b32_e32 v29, 6, v170
	v_lshlrev_b32_e32 v20, 3, v170
	v_lshlrev_b32_e32 v21, 4, v170
	v_readfirstlane_b32 s2, v29
	v_and_b32_e32 v22, 0x7f, v170
	v_lshlrev_b32_e32 v22, 3, v22
	v_lshlrev_b32_e32 v23, 3, v28
	s_lshr_b32 s0, s2, 1
	s_lshl_b32 s1, 2, s0
	s_mul_i32 s12, s0, 0x948000
	v_add_u32_e32 v22, s12, v22
	s_lshl_b32 s12, s2, 8
	v_lshl_add_u32 v24, v28, 2, s12
	v_mov_b32_e32 v25, s12
	s_sub_u32 s13, 16, s1
	s_lshl_b32 s41, s13, 2
	s_add_u32 s41, s41, s12
	v_mov_b32_e32 v26, s41
	s_add_u32 s40, s0, 1
	s_lshl_b32 s40, s40, 23
	s_sub_u32 s40, 0x3f800000, s40
	v_mov_b32_e32 v27, s40
	s_lshr_b32 s44, s76, 6
	s_and_b32 s45, s76, 63
	s_cmp_eq_u32 s45, 0
	s_cselect_b32 s38, 1, 0
	s_cmp_eq_u32 s45, 63
	s_cselect_b32 s39, 1, 0
	s_lshl_b32 s45, s45, 5
	s_lshl_b32 s50, s44, 11
	s_add_u32 s50, s50, s45
	s_sub_i32 s52, s50, 15
	s_sub_u32 s37, s1, 1
	s_cmp_eq_u32 s38, 1
	s_cselect_b32 s36, 15, s13
	s_cselect_b32 s37, s37, 0
	s_waitcnt lgkmcnt(0)
	s_lshl_b32 s12, s86, 13
	s_add_u32 s6, s6, s12
	s_addc_u32 s7, s7, 0
	s_add_u32 s14, s4, 0x13000000
	s_addc_u32 s15, s5, 0
	s_add_u32 s16, s4, 0x10800
	s_addc_u32 s17, s5, 0
	s_add_u32 s18, s4, 0x1d900000
	s_addc_u32 s19, s5, 0
	s_lshl_b32 s12, s52, 3
	s_ashr_i32 s13, s12, 31
	s_add_u32 s20, s16, s12
	s_addc_u32 s21, s17, s13
	global_load_dwordx2 v[28:29], v23, s[20:21]
	global_load_dwordx4 v[2:5], v21, s[6:7]
	s_mul_i32 s12, s52, 0x1080
	s_mul_hi_i32 s13, s52, 0x1080
	s_add_u32 s22, s14, s12
	s_addc_u32 s23, s15, s13
	s_add_u32 s24, s22, 0xf780
	s_addc_u32 s25, s23, 0
	s_sub_u32 s12, 16, s1
	s_mul_i32 s12, s12, 0x1080
	s_add_u32 s26, s22, s12
	s_addc_u32 s27, s23, 0
	s_mul_i32 s12, s50, 0x480
	s_add_u32 s28, s18, s12
	s_addc_u32 s29, s19, 0
	s_lshl_b32 s12, s86, 2
	s_add_u32 s12, s12, s44
	s_mul_i32 s12, s12, 0x1e000
	s_add_u32 s12, s12, 0x4200000
	s_add_u32 s30, s8, s12
	s_addc_u32 s31, s9, 0
	global_load_dwordx2 v[34:35], v20, s[22:23]
	s_add_u32 s22, s22, 0x1080
	s_addc_u32 s23, s23, 0
	global_load_dwordx2 v[36:37], v20, s[22:23]
	s_add_u32 s22, s22, 0x1080
	s_addc_u32 s23, s23, 0
	global_load_dwordx2 v[38:39], v20, s[22:23]
	s_add_u32 s22, s22, 0x1080
	s_addc_u32 s23, s23, 0
	global_load_dwordx2 v[40:41], v20, s[22:23]
	s_add_u32 s22, s22, 0x1080
	s_addc_u32 s23, s23, 0
	global_load_dwordx2 v[42:43], v20, s[22:23]
	s_add_u32 s22, s22, 0x1080
	s_addc_u32 s23, s23, 0
	global_load_dwordx2 v[44:45], v20, s[22:23]
	s_add_u32 s22, s22, 0x1080
	s_addc_u32 s23, s23, 0
	global_load_dwordx2 v[46:47], v20, s[22:23]
	s_add_u32 s22, s22, 0x1080
	s_addc_u32 s23, s23, 0
	global_load_dwordx2 v[48:49], v20, s[22:23]
	s_add_u32 s22, s22, 0x1080
	s_addc_u32 s23, s23, 0
	global_load_dwordx2 v[50:51], v20, s[22:23]
	s_add_u32 s22, s22, 0x1080
	s_addc_u32 s23, s23, 0
	global_load_dwordx2 v[52:53], v20, s[22:23]
	s_add_u32 s22, s22, 0x1080
	s_addc_u32 s23, s23, 0
	global_load_dwordx2 v[54:55], v20, s[22:23]
	s_add_u32 s22, s22, 0x1080
	s_addc_u32 s23, s23, 0
	global_load_dwordx2 v[56:57], v20, s[22:23]
	s_add_u32 s22, s22, 0x1080
	s_addc_u32 s23, s23, 0
	global_load_dwordx2 v[58:59], v20, s[22:23]
	s_add_u32 s22, s22, 0x1080
	s_addc_u32 s23, s23, 0
	global_load_dwordx2 v[60:61], v20, s[22:23]
	s_add_u32 s22, s22, 0x1080
	s_addc_u32 s23, s23, 0
	global_load_dwordx2 v[62:63], v20, s[22:23]
	s_add_u32 s22, s22, 0x1080
	s_addc_u32 s23, s23, 0
	global_load_dwordx2 v[64:65], v20, s[24:25]
	s_add_u32 s24, s24, 0x1080
	s_addc_u32 s25, s25, 0
	global_load_dwordx2 v[66:67], v20, s[24:25]
	s_add_u32 s24, s24, 0x1080
	s_addc_u32 s25, s25, 0
	global_load_dwordx2 v[68:69], v20, s[24:25]
	s_add_u32 s24, s24, 0x1080
	s_addc_u32 s25, s25, 0
	global_load_dwordx2 v[70:71], v20, s[24:25]
	s_add_u32 s24, s24, 0x1080
	s_addc_u32 s25, s25, 0
	global_load_dwordx2 v[72:73], v20, s[24:25]
	s_add_u32 s24, s24, 0x1080
	s_addc_u32 s25, s25, 0
	global_load_dwordx2 v[74:75], v20, s[24:25]
	s_add_u32 s24, s24, 0x1080
	s_addc_u32 s25, s25, 0
	global_load_dwordx2 v[76:77], v20, s[24:25]
	s_add_u32 s24, s24, 0x1080
	s_addc_u32 s25, s25, 0
	global_load_dwordx2 v[78:79], v20, s[24:25]
	s_add_u32 s24, s24, 0x1080
	s_addc_u32 s25, s25, 0
	global_load_dwordx2 v[80:81], v20, s[26:27]
	s_add_u32 s26, s26, 0x1080
	s_addc_u32 s27, s27, 0
	global_load_dwordx2 v[82:83], v20, s[26:27]
	s_add_u32 s26, s26, 0x1080
	s_addc_u32 s27, s27, 0
	global_load_dwordx2 v[84:85], v20, s[26:27]
	s_add_u32 s26, s26, 0x1080
	s_addc_u32 s27, s27, 0
	global_load_dwordx2 v[86:87], v20, s[26:27]
	s_add_u32 s26, s26, 0x1080
	s_addc_u32 s27, s27, 0
	global_load_dwordx2 v[88:89], v20, s[26:27]
	s_add_u32 s26, s26, 0x1080
	s_addc_u32 s27, s27, 0
	global_load_dwordx2 v[90:91], v20, s[26:27]
	s_add_u32 s26, s26, 0x1080
	s_addc_u32 s27, s27, 0
	global_load_dwordx2 v[92:93], v20, s[26:27]
	s_add_u32 s26, s26, 0x1080
	s_addc_u32 s27, s27, 0
	global_load_dwordx2 v[94:95], v20, s[26:27]
	s_add_u32 s26, s26, 0x1080
	s_addc_u32 s27, s27, 0
	global_load_dwordx2 v[96:97], v20, s[24:25]
	s_add_u32 s24, s24, 0x1080
	s_addc_u32 s25, s25, 0
	global_load_dwordx2 v[98:99], v20, s[24:25]
	s_add_u32 s24, s24, 0x1080
	s_addc_u32 s25, s25, 0
	global_load_dwordx2 v[100:101], v20, s[24:25]
	s_add_u32 s24, s24, 0x1080
	s_addc_u32 s25, s25, 0
	global_load_dwordx2 v[102:103], v20, s[24:25]
	s_add_u32 s24, s24, 0x1080
	s_addc_u32 s25, s25, 0
	global_load_dwordx2 v[104:105], v20, s[24:25]
	s_add_u32 s24, s24, 0x1080
	s_addc_u32 s25, s25, 0
	global_load_dwordx2 v[106:107], v20, s[24:25]
	s_add_u32 s24, s24, 0x1080
	s_addc_u32 s25, s25, 0
	global_load_dwordx2 v[108:109], v20, s[24:25]
	s_add_u32 s24, s24, 0x1080
	s_addc_u32 s25, s25, 0
	global_load_dwordx2 v[110:111], v20, s[24:25]
	s_add_u32 s24, s24, 0x1080
	s_addc_u32 s25, s25, 0
	global_load_dwordx2 v[112:113], v20, s[26:27]
	s_add_u32 s26, s26, 0x1080
	s_addc_u32 s27, s27, 0
	global_load_dwordx2 v[114:115], v20, s[26:27]
	s_add_u32 s26, s26, 0x1080
	s_addc_u32 s27, s27, 0
	global_load_dwordx2 v[116:117], v20, s[26:27]
	s_add_u32 s26, s26, 0x1080
	s_addc_u32 s27, s27, 0
	global_load_dwordx2 v[118:119], v20, s[26:27]
	s_add_u32 s26, s26, 0x1080
	s_addc_u32 s27, s27, 0
	global_load_dwordx2 v[120:121], v20, s[26:27]
	s_add_u32 s26, s26, 0x1080
	s_addc_u32 s27, s27, 0
	global_load_dwordx2 v[122:123], v20, s[26:27]
	s_add_u32 s26, s26, 0x1080
	s_addc_u32 s27, s27, 0
	global_load_dwordx2 v[124:125], v20, s[26:27]
	s_add_u32 s26, s26, 0x1080
	s_addc_u32 s27, s27, 0
	global_load_dwordx2 v[126:127], v20, s[26:27]
	s_add_u32 s26, s26, 0x1080
	s_addc_u32 s27, s27, 0
	s_waitcnt vmcnt(48)
	v_ffbh_u32_e32 v30, v29
	v_min_u32_e32 v30, 32, v30
	v_lshlrev_b64 v[28:29], v30, v[28:29]
	v_min_u32_e32 v28, 1, v28
	v_or_b32_e32 v28, v29, v28
	v_cvt_f32_u32_e32 v28, v28
	v_sub_u32_e32 v30, 32, v30
	v_ldexp_f32 v30, v28, v30
	v_mul_f32_e32 v30, 0x2f800000, v30
	v_fmamk_f32 v30, v30, 0x3a000000, v171
	v_mul_f32_e32 v28, 0x4f800000, v30
	v_cmp_gt_f32_e32 vcc, s51, v30
	s_nop 1
	v_cndmask_b32_e32 v30, v30, v28, vcc
	v_sqrt_f32_e32 v28, v30
	s_nop 0
	v_add_u32_e32 v29, -1, v28
	v_add_u32_e32 v31, 1, v28
	v_fma_f32 v32, -v29, v28, v30
	v_fma_f32 v33, -v31, v28, v30
	v_cmp_ge_f32_e64 s[34:35], 0, v32
	s_nop 1
	v_cndmask_b32_e64 v28, v28, v29, s[34:35]
	v_cmp_lt_f32_e64 s[34:35], 0, v33
	s_nop 1
	v_cndmask_b32_e64 v28, v28, v31, s[34:35]
	v_mul_f32_e32 v29, 0x37800000, v28
	v_cndmask_b32_e32 v28, v28, v29, vcc
	v_cmp_class_f32_e32 vcc, v30, v172
	s_nop 1
	v_cndmask_b32_e32 v30, v28, v30, vcc
	v_div_scale_f32 v28, s[34:35], v30, v30, 1.0
	v_rcp_f32_e32 v29, v28
	v_div_scale_f32 v31, vcc, 1.0, v30, 1.0
	v_fma_f32 v32, -v28, v29, 1.0
	v_fmac_f32_e32 v29, v32, v29
	v_mul_f32_e32 v32, v31, v29
	v_fma_f32 v33, -v28, v32, v31
	v_fmac_f32_e32 v32, v33, v29
	v_fma_f32 v28, -v28, v32, v31
	v_div_fmas_f32 v28, v28, v29, v32
	v_div_fixup_f32 v30, v28, v30, 1.0
	ds_write_b32 v24, v30
	s_waitcnt lgkmcnt(0)
	ds_read_b128 v[128:131], v25 offset:0
	ds_read_b128 v[132:135], v25 offset:16
	ds_read_b128 v[136:139], v25 offset:32
	ds_read_b128 v[142:145], v25 offset:48
	ds_read_b32 v146, v25 offset:60
	ds_read_b32 v147, v25 offset:64
	ds_read_b32 v148, v25 offset:68
	ds_read_b32 v149, v25 offset:72
	ds_read_b32 v150, v25 offset:76
	ds_read_b32 v151, v25 offset:80
	ds_read_b32 v152, v25 offset:84
	ds_read_b32 v153, v25 offset:88
	ds_read_b32 v154, v26 offset:0
	ds_read_b32 v155, v26 offset:4
	ds_read_b32 v156, v26 offset:8
	ds_read_b32 v157, v26 offset:12
	ds_read_b32 v158, v26 offset:16
	ds_read_b32 v159, v26 offset:20
	ds_read_b32 v160, v26 offset:24
	ds_read_b32 v162, v26 offset:28
	v_mov_b32_e32 v6, 0
	v_mov_b32_e32 v7, 0
	v_mov_b32_e32 v8, 0
	v_mov_b32_e32 v9, 0
	s_waitcnt vmcnt(16)
	s_waitcnt lgkmcnt(0)
	s_cmp_gt_u32 s36, 0
	s_cbranch_scc1 .Lpp_i0
	v_lshlrev_b32_e32 v14, 16, v34
	v_and_b32_e32 v15, 0xffff0000, v34
	v_lshlrev_b32_e32 v16, 16, v35
	v_and_b32_e32 v17, 0xffff0000, v35
	v_mul_f32_e32 v14, v128, v14
	v_mul_f32_e32 v15, v128, v15
	v_mul_f32_e32 v16, v128, v16
	v_mul_f32_e32 v17, v128, v17
	v_pk_mul_f32 v[14:15], v[2:3], v[14:15]
	v_pk_mul_f32 v[16:17], v[4:5], v[16:17]
	v_pk_add_f32 v[6:7], v[6:7], v[14:15]
	v_pk_add_f32 v[8:9], v[8:9], v[16:17]
.Lpp_i0:
	s_cmp_gt_u32 s36, 1
	s_cbranch_scc1 .Lpp_i1
	v_lshlrev_b32_e32 v14, 16, v36
	v_and_b32_e32 v15, 0xffff0000, v36
	v_lshlrev_b32_e32 v16, 16, v37
	v_and_b32_e32 v17, 0xffff0000, v37
	v_mul_f32_e32 v14, v129, v14
	v_mul_f32_e32 v15, v129, v15
	v_mul_f32_e32 v16, v129, v16
	v_mul_f32_e32 v17, v129, v17
	v_pk_mul_f32 v[14:15], v[2:3], v[14:15]
	v_pk_mul_f32 v[16:17], v[4:5], v[16:17]
	v_pk_add_f32 v[6:7], v[6:7], v[14:15]
	v_pk_add_f32 v[8:9], v[8:9], v[16:17]
.Lpp_i1:
	s_cmp_gt_u32 s36, 2
	s_cbranch_scc1 .Lpp_i2
	v_lshlrev_b32_e32 v14, 16, v38
	v_and_b32_e32 v15, 0xffff0000, v38
	v_lshlrev_b32_e32 v16, 16, v39
	v_and_b32_e32 v17, 0xffff0000, v39
	v_mul_f32_e32 v14, v130, v14
	v_mul_f32_e32 v15, v130, v15
	v_mul_f32_e32 v16, v130, v16
	v_mul_f32_e32 v17, v130, v17
	v_pk_mul_f32 v[14:15], v[2:3], v[14:15]
	v_pk_mul_f32 v[16:17], v[4:5], v[16:17]
	v_pk_add_f32 v[6:7], v[6:7], v[14:15]
	v_pk_add_f32 v[8:9], v[8:9], v[16:17]
.Lpp_i2:
	s_cmp_gt_u32 s36, 3
	s_cbranch_scc1 .Lpp_i3
	v_lshlrev_b32_e32 v14, 16, v40
	v_and_b32_e32 v15, 0xffff0000, v40
	v_lshlrev_b32_e32 v16, 16, v41
	v_and_b32_e32 v17, 0xffff0000, v41
	v_mul_f32_e32 v14, v131, v14
	v_mul_f32_e32 v15, v131, v15
	v_mul_f32_e32 v16, v131, v16
	v_mul_f32_e32 v17, v131, v17
	v_pk_mul_f32 v[14:15], v[2:3], v[14:15]
	v_pk_mul_f32 v[16:17], v[4:5], v[16:17]
	v_pk_add_f32 v[6:7], v[6:7], v[14:15]
	v_pk_add_f32 v[8:9], v[8:9], v[16:17]
.Lpp_i3:
	s_cmp_gt_u32 s36, 4
	s_cbranch_scc1 .Lpp_i4
	v_lshlrev_b32_e32 v14, 16, v42
	v_and_b32_e32 v15, 0xffff0000, v42
	v_lshlrev_b32_e32 v16, 16, v43
	v_and_b32_e32 v17, 0xffff0000, v43
	v_mul_f32_e32 v14, v132, v14
	v_mul_f32_e32 v15, v132, v15
	v_mul_f32_e32 v16, v132, v16
	v_mul_f32_e32 v17, v132, v17
	v_pk_mul_f32 v[14:15], v[2:3], v[14:15]
	v_pk_mul_f32 v[16:17], v[4:5], v[16:17]
	v_pk_add_f32 v[6:7], v[6:7], v[14:15]
	v_pk_add_f32 v[8:9], v[8:9], v[16:17]
.Lpp_i4:
	s_cmp_gt_u32 s36, 5
	s_cbranch_scc1 .Lpp_i5
	v_lshlrev_b32_e32 v14, 16, v44
	v_and_b32_e32 v15, 0xffff0000, v44
	v_lshlrev_b32_e32 v16, 16, v45
	v_and_b32_e32 v17, 0xffff0000, v45
	v_mul_f32_e32 v14, v133, v14
	v_mul_f32_e32 v15, v133, v15
	v_mul_f32_e32 v16, v133, v16
	v_mul_f32_e32 v17, v133, v17
	v_pk_mul_f32 v[14:15], v[2:3], v[14:15]
	v_pk_mul_f32 v[16:17], v[4:5], v[16:17]
	v_pk_add_f32 v[6:7], v[6:7], v[14:15]
	v_pk_add_f32 v[8:9], v[8:9], v[16:17]
.Lpp_i5:
	s_cmp_gt_u32 s36, 6
	s_cbranch_scc1 .Lpp_i6
	v_lshlrev_b32_e32 v14, 16, v46
	v_and_b32_e32 v15, 0xffff0000, v46
	v_lshlrev_b32_e32 v16, 16, v47
	v_and_b32_e32 v17, 0xffff0000, v47
	v_mul_f32_e32 v14, v134, v14
	v_mul_f32_e32 v15, v134, v15
	v_mul_f32_e32 v16, v134, v16
	v_mul_f32_e32 v17, v134, v17
	v_pk_mul_f32 v[14:15], v[2:3], v[14:15]
	v_pk_mul_f32 v[16:17], v[4:5], v[16:17]
	v_pk_add_f32 v[6:7], v[6:7], v[14:15]
	v_pk_add_f32 v[8:9], v[8:9], v[16:17]
.Lpp_i6:
	s_cmp_gt_u32 s36, 7
	s_cbranch_scc1 .Lpp_i7
	v_lshlrev_b32_e32 v14, 16, v48
	v_and_b32_e32 v15, 0xffff0000, v48
	v_lshlrev_b32_e32 v16, 16, v49
	v_and_b32_e32 v17, 0xffff0000, v49
	v_mul_f32_e32 v14, v135, v14
	v_mul_f32_e32 v15, v135, v15
	v_mul_f32_e32 v16, v135, v16
	v_mul_f32_e32 v17, v135, v17
	v_pk_mul_f32 v[14:15], v[2:3], v[14:15]
	v_pk_mul_f32 v[16:17], v[4:5], v[16:17]
	v_pk_add_f32 v[6:7], v[6:7], v[14:15]
	v_pk_add_f32 v[8:9], v[8:9], v[16:17]
.Lpp_i7:
	s_cmp_gt_u32 s36, 8
	s_cbranch_scc1 .Lpp_i8
	v_lshlrev_b32_e32 v14, 16, v50
	v_and_b32_e32 v15, 0xffff0000, v50
	v_lshlrev_b32_e32 v16, 16, v51
	v_and_b32_e32 v17, 0xffff0000, v51
	v_mul_f32_e32 v14, v136, v14
	v_mul_f32_e32 v15, v136, v15
	v_mul_f32_e32 v16, v136, v16
	v_mul_f32_e32 v17, v136, v17
	v_pk_mul_f32 v[14:15], v[2:3], v[14:15]
	v_pk_mul_f32 v[16:17], v[4:5], v[16:17]
	v_pk_add_f32 v[6:7], v[6:7], v[14:15]
	v_pk_add_f32 v[8:9], v[8:9], v[16:17]
.Lpp_i8:
	s_cmp_gt_u32 s36, 9
	s_cbranch_scc1 .Lpp_i9
	v_lshlrev_b32_e32 v14, 16, v52
	v_and_b32_e32 v15, 0xffff0000, v52
	v_lshlrev_b32_e32 v16, 16, v53
	v_and_b32_e32 v17, 0xffff0000, v53
	v_mul_f32_e32 v14, v137, v14
	v_mul_f32_e32 v15, v137, v15
	v_mul_f32_e32 v16, v137, v16
	v_mul_f32_e32 v17, v137, v17
	v_pk_mul_f32 v[14:15], v[2:3], v[14:15]
	v_pk_mul_f32 v[16:17], v[4:5], v[16:17]
	v_pk_add_f32 v[6:7], v[6:7], v[14:15]
	v_pk_add_f32 v[8:9], v[8:9], v[16:17]
.Lpp_i9:
	s_cmp_gt_u32 s36, 10
	s_cbranch_scc1 .Lpp_i10
	v_lshlrev_b32_e32 v14, 16, v54
	v_and_b32_e32 v15, 0xffff0000, v54
	v_lshlrev_b32_e32 v16, 16, v55
	v_and_b32_e32 v17, 0xffff0000, v55
	v_mul_f32_e32 v14, v138, v14
	v_mul_f32_e32 v15, v138, v15
	v_mul_f32_e32 v16, v138, v16
	v_mul_f32_e32 v17, v138, v17
	v_pk_mul_f32 v[14:15], v[2:3], v[14:15]
	v_pk_mul_f32 v[16:17], v[4:5], v[16:17]
	v_pk_add_f32 v[6:7], v[6:7], v[14:15]
	v_pk_add_f32 v[8:9], v[8:9], v[16:17]
.Lpp_i10:
	s_cmp_gt_u32 s36, 11
	s_cbranch_scc1 .Lpp_i11
	v_lshlrev_b32_e32 v14, 16, v56
	v_and_b32_e32 v15, 0xffff0000, v56
	v_lshlrev_b32_e32 v16, 16, v57
	v_and_b32_e32 v17, 0xffff0000, v57
	v_mul_f32_e32 v14, v139, v14
	v_mul_f32_e32 v15, v139, v15
	v_mul_f32_e32 v16, v139, v16
	v_mul_f32_e32 v17, v139, v17
	v_pk_mul_f32 v[14:15], v[2:3], v[14:15]
	v_pk_mul_f32 v[16:17], v[4:5], v[16:17]
	v_pk_add_f32 v[6:7], v[6:7], v[14:15]
	v_pk_add_f32 v[8:9], v[8:9], v[16:17]
.Lpp_i11:
	s_cmp_gt_u32 s36, 12
	s_cbranch_scc1 .Lpp_i12
	v_lshlrev_b32_e32 v14, 16, v58
	v_and_b32_e32 v15, 0xffff0000, v58
	v_lshlrev_b32_e32 v16, 16, v59
	v_and_b32_e32 v17, 0xffff0000, v59
	v_mul_f32_e32 v14, v142, v14
	v_mul_f32_e32 v15, v142, v15
	v_mul_f32_e32 v16, v142, v16
	v_mul_f32_e32 v17, v142, v17
	v_pk_mul_f32 v[14:15], v[2:3], v[14:15]
	v_pk_mul_f32 v[16:17], v[4:5], v[16:17]
	v_pk_add_f32 v[6:7], v[6:7], v[14:15]
	v_pk_add_f32 v[8:9], v[8:9], v[16:17]
.Lpp_i12:
	s_cmp_gt_u32 s36, 13
	s_cbranch_scc1 .Lpp_i13
	v_lshlrev_b32_e32 v14, 16, v60
	v_and_b32_e32 v15, 0xffff0000, v60
	v_lshlrev_b32_e32 v16, 16, v61
	v_and_b32_e32 v17, 0xffff0000, v61
	v_mul_f32_e32 v14, v143, v14
	v_mul_f32_e32 v15, v143, v15
	v_mul_f32_e32 v16, v143, v16
	v_mul_f32_e32 v17, v143, v17
	v_pk_mul_f32 v[14:15], v[2:3], v[14:15]
	v_pk_mul_f32 v[16:17], v[4:5], v[16:17]
	v_pk_add_f32 v[6:7], v[6:7], v[14:15]
	v_pk_add_f32 v[8:9], v[8:9], v[16:17]
.Lpp_i13:
	s_cmp_gt_u32 s36, 14
	s_cbranch_scc1 .Lpp_i14
	v_lshlrev_b32_e32 v14, 16, v62
	v_and_b32_e32 v15, 0xffff0000, v62
	v_lshlrev_b32_e32 v16, 16, v63
	v_and_b32_e32 v17, 0xffff0000, v63
	v_mul_f32_e32 v14, v144, v14
	v_mul_f32_e32 v15, v144, v15
	v_mul_f32_e32 v16, v144, v16
	v_mul_f32_e32 v17, v144, v17
	v_pk_mul_f32 v[14:15], v[2:3], v[14:15]
	v_pk_mul_f32 v[16:17], v[4:5], v[16:17]
	v_pk_add_f32 v[6:7], v[6:7], v[14:15]
	v_pk_add_f32 v[8:9], v[8:9], v[16:17]
.Lpp_i14:
	ds_read_b32 v128, v25 offset:92
	ds_read_b32 v129, v25 offset:96
	ds_read_b32 v130, v25 offset:100
	ds_read_b32 v131, v25 offset:104
	ds_read_b32 v132, v25 offset:108
	ds_read_b32 v133, v25 offset:112
	ds_read_b32 v134, v25 offset:116
	ds_read_b32 v135, v25 offset:120
	ds_read_b32 v136, v26 offset:32
	ds_read_b32 v137, v26 offset:36
	ds_read_b32 v138, v26 offset:40
	ds_read_b32 v139, v26 offset:44
	ds_read_b32 v142, v26 offset:48
	ds_read_b32 v143, v26 offset:52
	ds_read_b32 v144, v26 offset:56
	ds_read_b32 v145, v26 offset:60
	v_lshlrev_b32_e32 v10, 16, v64
	v_and_b32_e32 v11, 0xffff0000, v64
	v_lshlrev_b32_e32 v12, 16, v65
	v_and_b32_e32 v13, 0xffff0000, v65
	v_mul_f32_e32 v10, v146, v10
	v_mul_f32_e32 v11, v146, v11
	v_mul_f32_e32 v12, v146, v12
	v_mul_f32_e32 v13, v146, v13
	v_pk_mul_f32 v[10:11], v[2:3], v[10:11]
	v_pk_mul_f32 v[12:13], v[4:5], v[12:13]
	v_pk_add_f32 v[6:7], v[6:7], v[10:11]
	v_pk_add_f32 v[8:9], v[8:9], v[12:13]
	s_cmp_gt_u32 s37, 0
	s_cbranch_scc0 .Lpp_n0
	v_mov_b32_e32 v18, 0x3f800000
	v_pk_fma_f32 v[14:15], v[6:7], v[18:19], v[10:11] op_sel_hi:[1,0,1] neg_lo:[0,0,1] neg_hi:[0,0,1]
	v_pk_fma_f32 v[16:17], v[8:9], v[18:19], v[12:13] op_sel_hi:[1,0,1] neg_lo:[0,0,1] neg_hi:[0,0,1]
	v_cvt_pk_bf16_f32 v14, v14, v15
	v_cvt_pk_bf16_f32 v15, v16, v17
	global_store_dwordx2 v22, v[14:15], s[28:29]
	s_branch .Lpp_d0
.Lpp_n0:
	v_mov_b32_e32 v18, v27
	v_pk_fma_f32 v[14:15], v[6:7], v[18:19], v[10:11] op_sel_hi:[1,0,1] neg_lo:[0,0,1] neg_hi:[0,0,1]
	v_pk_fma_f32 v[16:17], v[8:9], v[18:19], v[12:13] op_sel_hi:[1,0,1] neg_lo:[0,0,1] neg_hi:[0,0,1]
	v_cvt_pk_bf16_f32 v14, v14, v15
	v_cvt_pk_bf16_f32 v15, v16, v17
	global_store_dwordx2 v22, v[14:15], s[28:29]
	v_lshlrev_b32_e32 v14, 16, v80
	v_and_b32_e32 v15, 0xffff0000, v80
	v_lshlrev_b32_e32 v16, 16, v81
	v_and_b32_e32 v17, 0xffff0000, v81
	v_mul_f32_e32 v14, v154, v14
	v_mul_f32_e32 v15, v154, v15
	v_mul_f32_e32 v16, v154, v16
	v_mul_f32_e32 v17, v154, v17
	v_pk_mul_f32 v[14:15], v[2:3], v[14:15]
	v_pk_mul_f32 v[16:17], v[4:5], v[16:17]
	v_pk_add_f32 v[6:7], v[6:7], v[14:15] neg_lo:[0,1] neg_hi:[0,1]
	v_pk_add_f32 v[8:9], v[8:9], v[16:17] neg_lo:[0,1] neg_hi:[0,1]
.Lpp_d0:
	s_add_u32 s28, s28, 0x480
	s_addc_u32 s29, s29, 0
	v_lshlrev_b32_e32 v10, 16, v66
	v_and_b32_e32 v11, 0xffff0000, v66
	v_lshlrev_b32_e32 v12, 16, v67
	v_and_b32_e32 v13, 0xffff0000, v67
	v_mul_f32_e32 v10, v147, v10
	v_mul_f32_e32 v11, v147, v11
	v_mul_f32_e32 v12, v147, v12
	v_mul_f32_e32 v13, v147, v13
	v_pk_mul_f32 v[10:11], v[2:3], v[10:11]
	v_pk_mul_f32 v[12:13], v[4:5], v[12:13]
	v_pk_add_f32 v[6:7], v[6:7], v[10:11]
	v_pk_add_f32 v[8:9], v[8:9], v[12:13]
	s_cmp_gt_u32 s37, 1
	s_cbranch_scc0 .Lpp_n1
	v_mov_b32_e32 v18, 0x3f000000
	v_pk_fma_f32 v[14:15], v[6:7], v[18:19], v[10:11] op_sel_hi:[1,0,1] neg_lo:[0,0,1] neg_hi:[0,0,1]
	v_pk_fma_f32 v[16:17], v[8:9], v[18:19], v[12:13] op_sel_hi:[1,0,1] neg_lo:[0,0,1] neg_hi:[0,0,1]
	v_cvt_pk_bf16_f32 v14, v14, v15
	v_cvt_pk_bf16_f32 v15, v16, v17
	global_store_dwordx2 v22, v[14:15], s[28:29]
	s_branch .Lpp_d1
.Lpp_n1:
	v_mov_b32_e32 v18, v27
	v_pk_fma_f32 v[14:15], v[6:7], v[18:19], v[10:11] op_sel_hi:[1,0,1] neg_lo:[0,0,1] neg_hi:[0,0,1]
	v_pk_fma_f32 v[16:17], v[8:9], v[18:19], v[12:13] op_sel_hi:[1,0,1] neg_lo:[0,0,1] neg_hi:[0,0,1]
	v_cvt_pk_bf16_f32 v14, v14, v15
	v_cvt_pk_bf16_f32 v15, v16, v17
	global_store_dwordx2 v22, v[14:15], s[28:29]
	v_lshlrev_b32_e32 v14, 16, v82
	v_and_b32_e32 v15, 0xffff0000, v82
	v_lshlrev_b32_e32 v16, 16, v83
	v_and_b32_e32 v17, 0xffff0000, v83
	v_mul_f32_e32 v14, v155, v14
	v_mul_f32_e32 v15, v155, v15
	v_mul_f32_e32 v16, v155, v16
	v_mul_f32_e32 v17, v155, v17
	v_pk_mul_f32 v[14:15], v[2:3], v[14:15]
	v_pk_mul_f32 v[16:17], v[4:5], v[16:17]
	v_pk_add_f32 v[6:7], v[6:7], v[14:15] neg_lo:[0,1] neg_hi:[0,1]
	v_pk_add_f32 v[8:9], v[8:9], v[16:17] neg_lo:[0,1] neg_hi:[0,1]
.Lpp_d1:
	s_add_u32 s28, s28, 0x480
	s_addc_u32 s29, s29, 0
	v_lshlrev_b32_e32 v10, 16, v68
	v_and_b32_e32 v11, 0xffff0000, v68
	v_lshlrev_b32_e32 v12, 16, v69
	v_and_b32_e32 v13, 0xffff0000, v69
	v_mul_f32_e32 v10, v148, v10
	v_mul_f32_e32 v11, v148, v11
	v_mul_f32_e32 v12, v148, v12
	v_mul_f32_e32 v13, v148, v13
	v_pk_mul_f32 v[10:11], v[2:3], v[10:11]
	v_pk_mul_f32 v[12:13], v[4:5], v[12:13]
	v_pk_add_f32 v[6:7], v[6:7], v[10:11]
	v_pk_add_f32 v[8:9], v[8:9], v[12:13]
	s_cmp_gt_u32 s37, 2
	s_cbranch_scc0 .Lpp_n2
	v_mov_b32_e32 v18, 0x3eaaaaab
	v_pk_fma_f32 v[14:15], v[6:7], v[18:19], v[10:11] op_sel_hi:[1,0,1] neg_lo:[0,0,1] neg_hi:[0,0,1]
	v_pk_fma_f32 v[16:17], v[8:9], v[18:19], v[12:13] op_sel_hi:[1,0,1] neg_lo:[0,0,1] neg_hi:[0,0,1]
	v_cvt_pk_bf16_f32 v14, v14, v15
	v_cvt_pk_bf16_f32 v15, v16, v17
	global_store_dwordx2 v22, v[14:15], s[28:29]
	s_branch .Lpp_d2
.Lpp_n2:
	v_mov_b32_e32 v18, v27
	v_pk_fma_f32 v[14:15], v[6:7], v[18:19], v[10:11] op_sel_hi:[1,0,1] neg_lo:[0,0,1] neg_hi:[0,0,1]
	v_pk_fma_f32 v[16:17], v[8:9], v[18:19], v[12:13] op_sel_hi:[1,0,1] neg_lo:[0,0,1] neg_hi:[0,0,1]
	v_cvt_pk_bf16_f32 v14, v14, v15
	v_cvt_pk_bf16_f32 v15, v16, v17
	global_store_dwordx2 v22, v[14:15], s[28:29]
	v_lshlrev_b32_e32 v14, 16, v84
	v_and_b32_e32 v15, 0xffff0000, v84
	v_lshlrev_b32_e32 v16, 16, v85
	v_and_b32_e32 v17, 0xffff0000, v85
	v_mul_f32_e32 v14, v156, v14
	v_mul_f32_e32 v15, v156, v15
	v_mul_f32_e32 v16, v156, v16
	v_mul_f32_e32 v17, v156, v17
	v_pk_mul_f32 v[14:15], v[2:3], v[14:15]
	v_pk_mul_f32 v[16:17], v[4:5], v[16:17]
	v_pk_add_f32 v[6:7], v[6:7], v[14:15] neg_lo:[0,1] neg_hi:[0,1]
	v_pk_add_f32 v[8:9], v[8:9], v[16:17] neg_lo:[0,1] neg_hi:[0,1]
.Lpp_d2:
	s_add_u32 s28, s28, 0x480
	s_addc_u32 s29, s29, 0
	v_lshlrev_b32_e32 v10, 16, v70
	v_and_b32_e32 v11, 0xffff0000, v70
	v_lshlrev_b32_e32 v12, 16, v71
	v_and_b32_e32 v13, 0xffff0000, v71
	v_mul_f32_e32 v10, v149, v10
	v_mul_f32_e32 v11, v149, v11
	v_mul_f32_e32 v12, v149, v12
	v_mul_f32_e32 v13, v149, v13
	v_pk_mul_f32 v[10:11], v[2:3], v[10:11]
	v_pk_mul_f32 v[12:13], v[4:5], v[12:13]
	v_pk_add_f32 v[6:7], v[6:7], v[10:11]
	v_pk_add_f32 v[8:9], v[8:9], v[12:13]
	s_cmp_gt_u32 s37, 3
	s_cbranch_scc0 .Lpp_n3
	v_mov_b32_e32 v18, 0x3e800000
	v_pk_fma_f32 v[14:15], v[6:7], v[18:19], v[10:11] op_sel_hi:[1,0,1] neg_lo:[0,0,1] neg_hi:[0,0,1]
	v_pk_fma_f32 v[16:17], v[8:9], v[18:19], v[12:13] op_sel_hi:[1,0,1] neg_lo:[0,0,1] neg_hi:[0,0,1]
	v_cvt_pk_bf16_f32 v14, v14, v15
	v_cvt_pk_bf16_f32 v15, v16, v17
	global_store_dwordx2 v22, v[14:15], s[28:29]
	s_branch .Lpp_d3
.Lpp_n3:
	v_mov_b32_e32 v18, v27
	v_pk_fma_f32 v[14:15], v[6:7], v[18:19], v[10:11] op_sel_hi:[1,0,1] neg_lo:[0,0,1] neg_hi:[0,0,1]
	v_pk_fma_f32 v[16:17], v[8:9], v[18:19], v[12:13] op_sel_hi:[1,0,1] neg_lo:[0,0,1] neg_hi:[0,0,1]
	v_cvt_pk_bf16_f32 v14, v14, v15
	v_cvt_pk_bf16_f32 v15, v16, v17
	global_store_dwordx2 v22, v[14:15], s[28:29]
	v_lshlrev_b32_e32 v14, 16, v86
	v_and_b32_e32 v15, 0xffff0000, v86
	v_lshlrev_b32_e32 v16, 16, v87
	v_and_b32_e32 v17, 0xffff0000, v87
	v_mul_f32_e32 v14, v157, v14
	v_mul_f32_e32 v15, v157, v15
	v_mul_f32_e32 v16, v157, v16
	v_mul_f32_e32 v17, v157, v17
	v_pk_mul_f32 v[14:15], v[2:3], v[14:15]
	v_pk_mul_f32 v[16:17], v[4:5], v[16:17]
	v_pk_add_f32 v[6:7], v[6:7], v[14:15] neg_lo:[0,1] neg_hi:[0,1]
	v_pk_add_f32 v[8:9], v[8:9], v[16:17] neg_lo:[0,1] neg_hi:[0,1]
.Lpp_d3:
	s_add_u32 s28, s28, 0x480
	s_addc_u32 s29, s29, 0
	v_lshlrev_b32_e32 v10, 16, v72
	v_and_b32_e32 v11, 0xffff0000, v72
	v_lshlrev_b32_e32 v12, 16, v73
	v_and_b32_e32 v13, 0xffff0000, v73
	v_mul_f32_e32 v10, v150, v10
	v_mul_f32_e32 v11, v150, v11
	v_mul_f32_e32 v12, v150, v12
	v_mul_f32_e32 v13, v150, v13
	v_pk_mul_f32 v[10:11], v[2:3], v[10:11]
	v_pk_mul_f32 v[12:13], v[4:5], v[12:13]
	v_pk_add_f32 v[6:7], v[6:7], v[10:11]
	v_pk_add_f32 v[8:9], v[8:9], v[12:13]
	s_cmp_gt_u32 s37, 4
	s_cbranch_scc0 .Lpp_n4
	v_mov_b32_e32 v18, 0x3e4ccccd
	v_pk_fma_f32 v[14:15], v[6:7], v[18:19], v[10:11] op_sel_hi:[1,0,1] neg_lo:[0,0,1] neg_hi:[0,0,1]
	v_pk_fma_f32 v[16:17], v[8:9], v[18:19], v[12:13] op_sel_hi:[1,0,1] neg_lo:[0,0,1] neg_hi:[0,0,1]
	v_cvt_pk_bf16_f32 v14, v14, v15
	v_cvt_pk_bf16_f32 v15, v16, v17
	global_store_dwordx2 v22, v[14:15], s[28:29]
	s_branch .Lpp_d4
.Lpp_n4:
	v_mov_b32_e32 v18, v27
	v_pk_fma_f32 v[14:15], v[6:7], v[18:19], v[10:11] op_sel_hi:[1,0,1] neg_lo:[0,0,1] neg_hi:[0,0,1]
	v_pk_fma_f32 v[16:17], v[8:9], v[18:19], v[12:13] op_sel_hi:[1,0,1] neg_lo:[0,0,1] neg_hi:[0,0,1]
	v_cvt_pk_bf16_f32 v14, v14, v15
	v_cvt_pk_bf16_f32 v15, v16, v17
	global_store_dwordx2 v22, v[14:15], s[28:29]
	v_lshlrev_b32_e32 v14, 16, v88
	v_and_b32_e32 v15, 0xffff0000, v88
	v_lshlrev_b32_e32 v16, 16, v89
	v_and_b32_e32 v17, 0xffff0000, v89
	v_mul_f32_e32 v14, v158, v14
	v_mul_f32_e32 v15, v158, v15
	v_mul_f32_e32 v16, v158, v16
	v_mul_f32_e32 v17, v158, v17
	v_pk_mul_f32 v[14:15], v[2:3], v[14:15]
	v_pk_mul_f32 v[16:17], v[4:5], v[16:17]
	v_pk_add_f32 v[6:7], v[6:7], v[14:15] neg_lo:[0,1] neg_hi:[0,1]
	v_pk_add_f32 v[8:9], v[8:9], v[16:17] neg_lo:[0,1] neg_hi:[0,1]
.Lpp_d4:
	s_add_u32 s28, s28, 0x480
	s_addc_u32 s29, s29, 0
	v_lshlrev_b32_e32 v10, 16, v74
	v_and_b32_e32 v11, 0xffff0000, v74
	v_lshlrev_b32_e32 v12, 16, v75
	v_and_b32_e32 v13, 0xffff0000, v75
	v_mul_f32_e32 v10, v151, v10
	v_mul_f32_e32 v11, v151, v11
	v_mul_f32_e32 v12, v151, v12
	v_mul_f32_e32 v13, v151, v13
	v_pk_mul_f32 v[10:11], v[2:3], v[10:11]
	v_pk_mul_f32 v[12:13], v[4:5], v[12:13]
	v_pk_add_f32 v[6:7], v[6:7], v[10:11]
	v_pk_add_f32 v[8:9], v[8:9], v[12:13]
	s_cmp_gt_u32 s37, 5
	s_cbranch_scc0 .Lpp_n5
	v_mov_b32_e32 v18, 0x3e2aaaab
	v_pk_fma_f32 v[14:15], v[6:7], v[18:19], v[10:11] op_sel_hi:[1,0,1] neg_lo:[0,0,1] neg_hi:[0,0,1]
	v_pk_fma_f32 v[16:17], v[8:9], v[18:19], v[12:13] op_sel_hi:[1,0,1] neg_lo:[0,0,1] neg_hi:[0,0,1]
	v_cvt_pk_bf16_f32 v14, v14, v15
	v_cvt_pk_bf16_f32 v15, v16, v17
	global_store_dwordx2 v22, v[14:15], s[28:29]
	s_branch .Lpp_d5
.Lpp_n5:
	v_mov_b32_e32 v18, v27
	v_pk_fma_f32 v[14:15], v[6:7], v[18:19], v[10:11] op_sel_hi:[1,0,1] neg_lo:[0,0,1] neg_hi:[0,0,1]
	v_pk_fma_f32 v[16:17], v[8:9], v[18:19], v[12:13] op_sel_hi:[1,0,1] neg_lo:[0,0,1] neg_hi:[0,0,1]
	v_cvt_pk_bf16_f32 v14, v14, v15
	v_cvt_pk_bf16_f32 v15, v16, v17
	global_store_dwordx2 v22, v[14:15], s[28:29]
	v_lshlrev_b32_e32 v14, 16, v90
	v_and_b32_e32 v15, 0xffff0000, v90
	v_lshlrev_b32_e32 v16, 16, v91
	v_and_b32_e32 v17, 0xffff0000, v91
	v_mul_f32_e32 v14, v159, v14
	v_mul_f32_e32 v15, v159, v15
	v_mul_f32_e32 v16, v159, v16
	v_mul_f32_e32 v17, v159, v17
	v_pk_mul_f32 v[14:15], v[2:3], v[14:15]
	v_pk_mul_f32 v[16:17], v[4:5], v[16:17]
	v_pk_add_f32 v[6:7], v[6:7], v[14:15] neg_lo:[0,1] neg_hi:[0,1]
	v_pk_add_f32 v[8:9], v[8:9], v[16:17] neg_lo:[0,1] neg_hi:[0,1]
.Lpp_d5:
	s_add_u32 s28, s28, 0x480
	s_addc_u32 s29, s29, 0
	v_lshlrev_b32_e32 v10, 16, v76
	v_and_b32_e32 v11, 0xffff0000, v76
	v_lshlrev_b32_e32 v12, 16, v77
	v_and_b32_e32 v13, 0xffff0000, v77
	v_mul_f32_e32 v10, v152, v10
	v_mul_f32_e32 v11, v152, v11
	v_mul_f32_e32 v12, v152, v12
	v_mul_f32_e32 v13, v152, v13
	v_pk_mul_f32 v[10:11], v[2:3], v[10:11]
	v_pk_mul_f32 v[12:13], v[4:5], v[12:13]
	v_pk_add_f32 v[6:7], v[6:7], v[10:11]
	v_pk_add_f32 v[8:9], v[8:9], v[12:13]
	s_cmp_gt_u32 s37, 6
	s_cbranch_scc0 .Lpp_n6
	v_mov_b32_e32 v18, 0x3e124925
	v_pk_fma_f32 v[14:15], v[6:7], v[18:19], v[10:11] op_sel_hi:[1,0,1] neg_lo:[0,0,1] neg_hi:[0,0,1]
	v_pk_fma_f32 v[16:17], v[8:9], v[18:19], v[12:13] op_sel_hi:[1,0,1] neg_lo:[0,0,1] neg_hi:[0,0,1]
	v_cvt_pk_bf16_f32 v14, v14, v15
	v_cvt_pk_bf16_f32 v15, v16, v17
	global_store_dwordx2 v22, v[14:15], s[28:29]
	s_branch .Lpp_d6
.Lpp_n6:
	v_mov_b32_e32 v18, v27
	v_pk_fma_f32 v[14:15], v[6:7], v[18:19], v[10:11] op_sel_hi:[1,0,1] neg_lo:[0,0,1] neg_hi:[0,0,1]
	v_pk_fma_f32 v[16:17], v[8:9], v[18:19], v[12:13] op_sel_hi:[1,0,1] neg_lo:[0,0,1] neg_hi:[0,0,1]
	v_cvt_pk_bf16_f32 v14, v14, v15
	v_cvt_pk_bf16_f32 v15, v16, v17
	global_store_dwordx2 v22, v[14:15], s[28:29]
	v_lshlrev_b32_e32 v14, 16, v92
	v_and_b32_e32 v15, 0xffff0000, v92
	v_lshlrev_b32_e32 v16, 16, v93
	v_and_b32_e32 v17, 0xffff0000, v93
	v_mul_f32_e32 v14, v160, v14
	v_mul_f32_e32 v15, v160, v15
	v_mul_f32_e32 v16, v160, v16
	v_mul_f32_e32 v17, v160, v17
	v_pk_mul_f32 v[14:15], v[2:3], v[14:15]
	v_pk_mul_f32 v[16:17], v[4:5], v[16:17]
	v_pk_add_f32 v[6:7], v[6:7], v[14:15] neg_lo:[0,1] neg_hi:[0,1]
	v_pk_add_f32 v[8:9], v[8:9], v[16:17] neg_lo:[0,1] neg_hi:[0,1]
.Lpp_d6:
	s_add_u32 s28, s28, 0x480
	s_addc_u32 s29, s29, 0
	v_lshlrev_b32_e32 v10, 16, v78
	v_and_b32_e32 v11, 0xffff0000, v78
	v_lshlrev_b32_e32 v12, 16, v79
	v_and_b32_e32 v13, 0xffff0000, v79
	v_mul_f32_e32 v10, v153, v10
	v_mul_f32_e32 v11, v153, v11
	v_mul_f32_e32 v12, v153, v12
	v_mul_f32_e32 v13, v153, v13
	v_pk_mul_f32 v[10:11], v[2:3], v[10:11]
	v_pk_mul_f32 v[12:13], v[4:5], v[12:13]
	v_pk_add_f32 v[6:7], v[6:7], v[10:11]
	v_pk_add_f32 v[8:9], v[8:9], v[12:13]
	s_cmp_gt_u32 s37, 7
	s_cbranch_scc0 .Lpp_n7
	v_mov_b32_e32 v18, 0x3e000000
	v_pk_fma_f32 v[14:15], v[6:7], v[18:19], v[10:11] op_sel_hi:[1,0,1] neg_lo:[0,0,1] neg_hi:[0,0,1]
	v_pk_fma_f32 v[16:17], v[8:9], v[18:19], v[12:13] op_sel_hi:[1,0,1] neg_lo:[0,0,1] neg_hi:[0,0,1]
	v_cvt_pk_bf16_f32 v14, v14, v15
	v_cvt_pk_bf16_f32 v15, v16, v17
	global_store_dwordx2 v22, v[14:15], s[28:29]
	s_branch .Lpp_d7
.Lpp_n7:
	v_mov_b32_e32 v18, v27
	v_pk_fma_f32 v[14:15], v[6:7], v[18:19], v[10:11] op_sel_hi:[1,0,1] neg_lo:[0,0,1] neg_hi:[0,0,1]
	v_pk_fma_f32 v[16:17], v[8:9], v[18:19], v[12:13] op_sel_hi:[1,0,1] neg_lo:[0,0,1] neg_hi:[0,0,1]
	v_cvt_pk_bf16_f32 v14, v14, v15
	v_cvt_pk_bf16_f32 v15, v16, v17
	global_store_dwordx2 v22, v[14:15], s[28:29]
	v_lshlrev_b32_e32 v14, 16, v94
	v_and_b32_e32 v15, 0xffff0000, v94
	v_lshlrev_b32_e32 v16, 16, v95
	v_and_b32_e32 v17, 0xffff0000, v95
	v_mul_f32_e32 v14, v162, v14
	v_mul_f32_e32 v15, v162, v15
	v_mul_f32_e32 v16, v162, v16
	v_mul_f32_e32 v17, v162, v17
	v_pk_mul_f32 v[14:15], v[2:3], v[14:15]
	v_pk_mul_f32 v[16:17], v[4:5], v[16:17]
	v_pk_add_f32 v[6:7], v[6:7], v[14:15] neg_lo:[0,1] neg_hi:[0,1]
	v_pk_add_f32 v[8:9], v[8:9], v[16:17] neg_lo:[0,1] neg_hi:[0,1]
.Lpp_d7:
	s_add_u32 s28, s28, 0x480
	s_addc_u32 s29, s29, 0
	global_load_dwordx2 v[64:65], v20, s[24:25]
	s_add_u32 s24, s24, 0x1080
	s_addc_u32 s25, s25, 0
	global_load_dwordx2 v[66:67], v20, s[24:25]
	s_add_u32 s24, s24, 0x1080
	s_addc_u32 s25, s25, 0
	global_load_dwordx2 v[68:69], v20, s[24:25]
	s_add_u32 s24, s24, 0x1080
	s_addc_u32 s25, s25, 0
	global_load_dwordx2 v[70:71], v20, s[24:25]
	s_add_u32 s24, s24, 0x1080
	s_addc_u32 s25, s25, 0
	global_load_dwordx2 v[72:73], v20, s[24:25]
	s_add_u32 s24, s24, 0x1080
	s_addc_u32 s25, s25, 0
	global_load_dwordx2 v[74:75], v20, s[24:25]
	s_add_u32 s24, s24, 0x1080
	s_addc_u32 s25, s25, 0
	global_load_dwordx2 v[76:77], v20, s[24:25]
	s_add_u32 s24, s24, 0x1080
	s_addc_u32 s25, s25, 0
	global_load_dwordx2 v[78:79], v20, s[24:25]
	s_add_u32 s24, s24, 0x1080
	s_addc_u32 s25, s25, 0
	global_load_dwordx2 v[80:81], v20, s[26:27]
	s_add_u32 s26, s26, 0x1080
	s_addc_u32 s27, s27, 0
	global_load_dwordx2 v[82:83], v20, s[26:27]
	s_add_u32 s26, s26, 0x1080
	s_addc_u32 s27, s27, 0
	global_load_dwordx2 v[84:85], v20, s[26:27]
	s_add_u32 s26, s26, 0x1080
	s_addc_u32 s27, s27, 0
	global_load_dwordx2 v[86:87], v20, s[26:27]
	s_add_u32 s26, s26, 0x1080
	s_addc_u32 s27, s27, 0
	global_load_dwordx2 v[88:89], v20, s[26:27]
	s_add_u32 s26, s26, 0x1080
	s_addc_u32 s27, s27, 0
	global_load_dwordx2 v[90:91], v20, s[26:27]
	s_add_u32 s26, s26, 0x1080
	s_addc_u32 s27, s27, 0
	global_load_dwordx2 v[92:93], v20, s[26:27]
	s_add_u32 s26, s26, 0x1080
	s_addc_u32 s27, s27, 0
	global_load_dwordx2 v[94:95], v20, s[26:27]
	s_add_u32 s26, s26, 0x1080
	s_addc_u32 s27, s27, 0
	ds_read_b32 v146, v25 offset:124
	ds_read_b32 v147, v25 offset:128
	ds_read_b32 v148, v25 offset:132
	ds_read_b32 v149, v25 offset:136
	ds_read_b32 v150, v25 offset:140
	ds_read_b32 v151, v25 offset:144
	ds_read_b32 v152, v25 offset:148
	ds_read_b32 v153, v25 offset:152
	ds_read_b32 v154, v26 offset:64
	ds_read_b32 v155, v26 offset:68
	ds_read_b32 v156, v26 offset:72
	ds_read_b32 v157, v26 offset:76
	ds_read_b32 v158, v26 offset:80
	ds_read_b32 v159, v26 offset:84
	ds_read_b32 v160, v26 offset:88
	ds_read_b32 v162, v26 offset:92
	s_waitcnt vmcnt(24)
	s_waitcnt lgkmcnt(0)
	v_lshlrev_b32_e32 v10, 16, v96
	v_and_b32_e32 v11, 0xffff0000, v96
	v_lshlrev_b32_e32 v12, 16, v97
	v_and_b32_e32 v13, 0xffff0000, v97
	v_mul_f32_e32 v10, v128, v10
	v_mul_f32_e32 v11, v128, v11
	v_mul_f32_e32 v12, v128, v12
	v_mul_f32_e32 v13, v128, v13
	v_pk_mul_f32 v[10:11], v[2:3], v[10:11]
	v_pk_mul_f32 v[12:13], v[4:5], v[12:13]
	v_pk_add_f32 v[6:7], v[6:7], v[10:11]
	v_pk_add_f32 v[8:9], v[8:9], v[12:13]
	s_cmp_gt_u32 s37, 8
	s_cbranch_scc0 .Lpp_n8
	v_mov_b32_e32 v18, 0x3de38e39
	v_pk_fma_f32 v[14:15], v[6:7], v[18:19], v[10:11] op_sel_hi:[1,0,1] neg_lo:[0,0,1] neg_hi:[0,0,1]
	v_pk_fma_f32 v[16:17], v[8:9], v[18:19], v[12:13] op_sel_hi:[1,0,1] neg_lo:[0,0,1] neg_hi:[0,0,1]
	v_cvt_pk_bf16_f32 v14, v14, v15
	v_cvt_pk_bf16_f32 v15, v16, v17
	global_store_dwordx2 v22, v[14:15], s[28:29]
	s_branch .Lpp_d8
.Lpp_n8:
	v_mov_b32_e32 v18, v27
	v_pk_fma_f32 v[14:15], v[6:7], v[18:19], v[10:11] op_sel_hi:[1,0,1] neg_lo:[0,0,1] neg_hi:[0,0,1]
	v_pk_fma_f32 v[16:17], v[8:9], v[18:19], v[12:13] op_sel_hi:[1,0,1] neg_lo:[0,0,1] neg_hi:[0,0,1]
	v_cvt_pk_bf16_f32 v14, v14, v15
	v_cvt_pk_bf16_f32 v15, v16, v17
	global_store_dwordx2 v22, v[14:15], s[28:29]
	v_lshlrev_b32_e32 v14, 16, v112
	v_and_b32_e32 v15, 0xffff0000, v112
	v_lshlrev_b32_e32 v16, 16, v113
	v_and_b32_e32 v17, 0xffff0000, v113
	v_mul_f32_e32 v14, v136, v14
	v_mul_f32_e32 v15, v136, v15
	v_mul_f32_e32 v16, v136, v16
	v_mul_f32_e32 v17, v136, v17
	v_pk_mul_f32 v[14:15], v[2:3], v[14:15]
	v_pk_mul_f32 v[16:17], v[4:5], v[16:17]
	v_pk_add_f32 v[6:7], v[6:7], v[14:15] neg_lo:[0,1] neg_hi:[0,1]
	v_pk_add_f32 v[8:9], v[8:9], v[16:17] neg_lo:[0,1] neg_hi:[0,1]
.Lpp_d8:
	s_add_u32 s28, s28, 0x480
	s_addc_u32 s29, s29, 0
	v_lshlrev_b32_e32 v10, 16, v98
	v_and_b32_e32 v11, 0xffff0000, v98
	v_lshlrev_b32_e32 v12, 16, v99
	v_and_b32_e32 v13, 0xffff0000, v99
	v_mul_f32_e32 v10, v129, v10
	v_mul_f32_e32 v11, v129, v11
	v_mul_f32_e32 v12, v129, v12
	v_mul_f32_e32 v13, v129, v13
	v_pk_mul_f32 v[10:11], v[2:3], v[10:11]
	v_pk_mul_f32 v[12:13], v[4:5], v[12:13]
	v_pk_add_f32 v[6:7], v[6:7], v[10:11]
	v_pk_add_f32 v[8:9], v[8:9], v[12:13]
	s_cmp_gt_u32 s37, 9
	s_cbranch_scc0 .Lpp_n9
	v_mov_b32_e32 v18, 0x3dcccccd
	v_pk_fma_f32 v[14:15], v[6:7], v[18:19], v[10:11] op_sel_hi:[1,0,1] neg_lo:[0,0,1] neg_hi:[0,0,1]
	v_pk_fma_f32 v[16:17], v[8:9], v[18:19], v[12:13] op_sel_hi:[1,0,1] neg_lo:[0,0,1] neg_hi:[0,0,1]
	v_cvt_pk_bf16_f32 v14, v14, v15
	v_cvt_pk_bf16_f32 v15, v16, v17
	global_store_dwordx2 v22, v[14:15], s[28:29]
	s_branch .Lpp_d9
.Lpp_n9:
	v_mov_b32_e32 v18, v27
	v_pk_fma_f32 v[14:15], v[6:7], v[18:19], v[10:11] op_sel_hi:[1,0,1] neg_lo:[0,0,1] neg_hi:[0,0,1]
	v_pk_fma_f32 v[16:17], v[8:9], v[18:19], v[12:13] op_sel_hi:[1,0,1] neg_lo:[0,0,1] neg_hi:[0,0,1]
	v_cvt_pk_bf16_f32 v14, v14, v15
	v_cvt_pk_bf16_f32 v15, v16, v17
	global_store_dwordx2 v22, v[14:15], s[28:29]
	v_lshlrev_b32_e32 v14, 16, v114
	v_and_b32_e32 v15, 0xffff0000, v114
	v_lshlrev_b32_e32 v16, 16, v115
	v_and_b32_e32 v17, 0xffff0000, v115
	v_mul_f32_e32 v14, v137, v14
	v_mul_f32_e32 v15, v137, v15
	v_mul_f32_e32 v16, v137, v16
	v_mul_f32_e32 v17, v137, v17
	v_pk_mul_f32 v[14:15], v[2:3], v[14:15]
	v_pk_mul_f32 v[16:17], v[4:5], v[16:17]
	v_pk_add_f32 v[6:7], v[6:7], v[14:15] neg_lo:[0,1] neg_hi:[0,1]
	v_pk_add_f32 v[8:9], v[8:9], v[16:17] neg_lo:[0,1] neg_hi:[0,1]
.Lpp_d9:
	s_add_u32 s28, s28, 0x480
	s_addc_u32 s29, s29, 0
	v_lshlrev_b32_e32 v10, 16, v100
	v_and_b32_e32 v11, 0xffff0000, v100
	v_lshlrev_b32_e32 v12, 16, v101
	v_and_b32_e32 v13, 0xffff0000, v101
	v_mul_f32_e32 v10, v130, v10
	v_mul_f32_e32 v11, v130, v11
	v_mul_f32_e32 v12, v130, v12
	v_mul_f32_e32 v13, v130, v13
	v_pk_mul_f32 v[10:11], v[2:3], v[10:11]
	v_pk_mul_f32 v[12:13], v[4:5], v[12:13]
	v_pk_add_f32 v[6:7], v[6:7], v[10:11]
	v_pk_add_f32 v[8:9], v[8:9], v[12:13]
	s_cmp_gt_u32 s37, 10
	s_cbranch_scc0 .Lpp_n10
	v_mov_b32_e32 v18, 0x3dba2e8c
	v_pk_fma_f32 v[14:15], v[6:7], v[18:19], v[10:11] op_sel_hi:[1,0,1] neg_lo:[0,0,1] neg_hi:[0,0,1]
	v_pk_fma_f32 v[16:17], v[8:9], v[18:19], v[12:13] op_sel_hi:[1,0,1] neg_lo:[0,0,1] neg_hi:[0,0,1]
	v_cvt_pk_bf16_f32 v14, v14, v15
	v_cvt_pk_bf16_f32 v15, v16, v17
	global_store_dwordx2 v22, v[14:15], s[28:29]
	s_branch .Lpp_d10
.Lpp_n10:
	v_mov_b32_e32 v18, v27
	v_pk_fma_f32 v[14:15], v[6:7], v[18:19], v[10:11] op_sel_hi:[1,0,1] neg_lo:[0,0,1] neg_hi:[0,0,1]
	v_pk_fma_f32 v[16:17], v[8:9], v[18:19], v[12:13] op_sel_hi:[1,0,1] neg_lo:[0,0,1] neg_hi:[0,0,1]
	v_cvt_pk_bf16_f32 v14, v14, v15
	v_cvt_pk_bf16_f32 v15, v16, v17
	global_store_dwordx2 v22, v[14:15], s[28:29]
	v_lshlrev_b32_e32 v14, 16, v116
	v_and_b32_e32 v15, 0xffff0000, v116
	v_lshlrev_b32_e32 v16, 16, v117
	v_and_b32_e32 v17, 0xffff0000, v117
	v_mul_f32_e32 v14, v138, v14
	v_mul_f32_e32 v15, v138, v15
	v_mul_f32_e32 v16, v138, v16
	v_mul_f32_e32 v17, v138, v17
	v_pk_mul_f32 v[14:15], v[2:3], v[14:15]
	v_pk_mul_f32 v[16:17], v[4:5], v[16:17]
	v_pk_add_f32 v[6:7], v[6:7], v[14:15] neg_lo:[0,1] neg_hi:[0,1]
	v_pk_add_f32 v[8:9], v[8:9], v[16:17] neg_lo:[0,1] neg_hi:[0,1]
.Lpp_d10:
	s_add_u32 s28, s28, 0x480
	s_addc_u32 s29, s29, 0
	v_lshlrev_b32_e32 v10, 16, v102
	v_and_b32_e32 v11, 0xffff0000, v102
	v_lshlrev_b32_e32 v12, 16, v103
	v_and_b32_e32 v13, 0xffff0000, v103
	v_mul_f32_e32 v10, v131, v10
	v_mul_f32_e32 v11, v131, v11
	v_mul_f32_e32 v12, v131, v12
	v_mul_f32_e32 v13, v131, v13
	v_pk_mul_f32 v[10:11], v[2:3], v[10:11]
	v_pk_mul_f32 v[12:13], v[4:5], v[12:13]
	v_pk_add_f32 v[6:7], v[6:7], v[10:11]
	v_pk_add_f32 v[8:9], v[8:9], v[12:13]
	s_cmp_gt_u32 s37, 11
	s_cbranch_scc0 .Lpp_n11
	v_mov_b32_e32 v18, 0x3daaaaab
	v_pk_fma_f32 v[14:15], v[6:7], v[18:19], v[10:11] op_sel_hi:[1,0,1] neg_lo:[0,0,1] neg_hi:[0,0,1]
	v_pk_fma_f32 v[16:17], v[8:9], v[18:19], v[12:13] op_sel_hi:[1,0,1] neg_lo:[0,0,1] neg_hi:[0,0,1]
	v_cvt_pk_bf16_f32 v14, v14, v15
	v_cvt_pk_bf16_f32 v15, v16, v17
	global_store_dwordx2 v22, v[14:15], s[28:29]
	s_branch .Lpp_d11
.Lpp_n11:
	v_mov_b32_e32 v18, v27
	v_pk_fma_f32 v[14:15], v[6:7], v[18:19], v[10:11] op_sel_hi:[1,0,1] neg_lo:[0,0,1] neg_hi:[0,0,1]
	v_pk_fma_f32 v[16:17], v[8:9], v[18:19], v[12:13] op_sel_hi:[1,0,1] neg_lo:[0,0,1] neg_hi:[0,0,1]
	v_cvt_pk_bf16_f32 v14, v14, v15
	v_cvt_pk_bf16_f32 v15, v16, v17
	global_store_dwordx2 v22, v[14:15], s[28:29]
	v_lshlrev_b32_e32 v14, 16, v118
	v_and_b32_e32 v15, 0xffff0000, v118
	v_lshlrev_b32_e32 v16, 16, v119
	v_and_b32_e32 v17, 0xffff0000, v119
	v_mul_f32_e32 v14, v139, v14
	v_mul_f32_e32 v15, v139, v15
	v_mul_f32_e32 v16, v139, v16
	v_mul_f32_e32 v17, v139, v17
	v_pk_mul_f32 v[14:15], v[2:3], v[14:15]
	v_pk_mul_f32 v[16:17], v[4:5], v[16:17]
	v_pk_add_f32 v[6:7], v[6:7], v[14:15] neg_lo:[0,1] neg_hi:[0,1]
	v_pk_add_f32 v[8:9], v[8:9], v[16:17] neg_lo:[0,1] neg_hi:[0,1]
.Lpp_d11:
	s_add_u32 s28, s28, 0x480
	s_addc_u32 s29, s29, 0
	v_lshlrev_b32_e32 v10, 16, v104
	v_and_b32_e32 v11, 0xffff0000, v104
	v_lshlrev_b32_e32 v12, 16, v105
	v_and_b32_e32 v13, 0xffff0000, v105
	v_mul_f32_e32 v10, v132, v10
	v_mul_f32_e32 v11, v132, v11
	v_mul_f32_e32 v12, v132, v12
	v_mul_f32_e32 v13, v132, v13
	v_pk_mul_f32 v[10:11], v[2:3], v[10:11]
	v_pk_mul_f32 v[12:13], v[4:5], v[12:13]
	v_pk_add_f32 v[6:7], v[6:7], v[10:11]
	v_pk_add_f32 v[8:9], v[8:9], v[12:13]
	s_cmp_gt_u32 s37, 12
	s_cbranch_scc0 .Lpp_n12
	v_mov_b32_e32 v18, 0x3d9d89d9
	v_pk_fma_f32 v[14:15], v[6:7], v[18:19], v[10:11] op_sel_hi:[1,0,1] neg_lo:[0,0,1] neg_hi:[0,0,1]
	v_pk_fma_f32 v[16:17], v[8:9], v[18:19], v[12:13] op_sel_hi:[1,0,1] neg_lo:[0,0,1] neg_hi:[0,0,1]
	v_cvt_pk_bf16_f32 v14, v14, v15
	v_cvt_pk_bf16_f32 v15, v16, v17
	global_store_dwordx2 v22, v[14:15], s[28:29]
	s_branch .Lpp_d12
.Lpp_n12:
	v_mov_b32_e32 v18, v27
	v_pk_fma_f32 v[14:15], v[6:7], v[18:19], v[10:11] op_sel_hi:[1,0,1] neg_lo:[0,0,1] neg_hi:[0,0,1]
	v_pk_fma_f32 v[16:17], v[8:9], v[18:19], v[12:13] op_sel_hi:[1,0,1] neg_lo:[0,0,1] neg_hi:[0,0,1]
	v_cvt_pk_bf16_f32 v14, v14, v15
	v_cvt_pk_bf16_f32 v15, v16, v17
	global_store_dwordx2 v22, v[14:15], s[28:29]
	v_lshlrev_b32_e32 v14, 16, v120
	v_and_b32_e32 v15, 0xffff0000, v120
	v_lshlrev_b32_e32 v16, 16, v121
	v_and_b32_e32 v17, 0xffff0000, v121
	v_mul_f32_e32 v14, v142, v14
	v_mul_f32_e32 v15, v142, v15
	v_mul_f32_e32 v16, v142, v16
	v_mul_f32_e32 v17, v142, v17
	v_pk_mul_f32 v[14:15], v[2:3], v[14:15]
	v_pk_mul_f32 v[16:17], v[4:5], v[16:17]
	v_pk_add_f32 v[6:7], v[6:7], v[14:15] neg_lo:[0,1] neg_hi:[0,1]
	v_pk_add_f32 v[8:9], v[8:9], v[16:17] neg_lo:[0,1] neg_hi:[0,1]
.Lpp_d12:
	s_add_u32 s28, s28, 0x480
	s_addc_u32 s29, s29, 0
	v_lshlrev_b32_e32 v10, 16, v106
	v_and_b32_e32 v11, 0xffff0000, v106
	v_lshlrev_b32_e32 v12, 16, v107
	v_and_b32_e32 v13, 0xffff0000, v107
	v_mul_f32_e32 v10, v133, v10
	v_mul_f32_e32 v11, v133, v11
	v_mul_f32_e32 v12, v133, v12
	v_mul_f32_e32 v13, v133, v13
	v_pk_mul_f32 v[10:11], v[2:3], v[10:11]
	v_pk_mul_f32 v[12:13], v[4:5], v[12:13]
	v_pk_add_f32 v[6:7], v[6:7], v[10:11]
	v_pk_add_f32 v[8:9], v[8:9], v[12:13]
	s_cmp_gt_u32 s37, 13
	s_cbranch_scc0 .Lpp_n13
	v_mov_b32_e32 v18, 0x3d924925
	v_pk_fma_f32 v[14:15], v[6:7], v[18:19], v[10:11] op_sel_hi:[1,0,1] neg_lo:[0,0,1] neg_hi:[0,0,1]
	v_pk_fma_f32 v[16:17], v[8:9], v[18:19], v[12:13] op_sel_hi:[1,0,1] neg_lo:[0,0,1] neg_hi:[0,0,1]
	v_cvt_pk_bf16_f32 v14, v14, v15
	v_cvt_pk_bf16_f32 v15, v16, v17
	global_store_dwordx2 v22, v[14:15], s[28:29]
	s_branch .Lpp_d13
.Lpp_n13:
	v_mov_b32_e32 v18, v27
	v_pk_fma_f32 v[14:15], v[6:7], v[18:19], v[10:11] op_sel_hi:[1,0,1] neg_lo:[0,0,1] neg_hi:[0,0,1]
	v_pk_fma_f32 v[16:17], v[8:9], v[18:19], v[12:13] op_sel_hi:[1,0,1] neg_lo:[0,0,1] neg_hi:[0,0,1]
	v_cvt_pk_bf16_f32 v14, v14, v15
	v_cvt_pk_bf16_f32 v15, v16, v17
	global_store_dwordx2 v22, v[14:15], s[28:29]
	v_lshlrev_b32_e32 v14, 16, v122
	v_and_b32_e32 v15, 0xffff0000, v122
	v_lshlrev_b32_e32 v16, 16, v123
	v_and_b32_e32 v17, 0xffff0000, v123
	v_mul_f32_e32 v14, v143, v14
	v_mul_f32_e32 v15, v143, v15
	v_mul_f32_e32 v16, v143, v16
	v_mul_f32_e32 v17, v143, v17
	v_pk_mul_f32 v[14:15], v[2:3], v[14:15]
	v_pk_mul_f32 v[16:17], v[4:5], v[16:17]
	v_pk_add_f32 v[6:7], v[6:7], v[14:15] neg_lo:[0,1] neg_hi:[0,1]
	v_pk_add_f32 v[8:9], v[8:9], v[16:17] neg_lo:[0,1] neg_hi:[0,1]
.Lpp_d13:
	s_add_u32 s28, s28, 0x480
	s_addc_u32 s29, s29, 0
	v_lshlrev_b32_e32 v10, 16, v108
	v_and_b32_e32 v11, 0xffff0000, v108
	v_lshlrev_b32_e32 v12, 16, v109
	v_and_b32_e32 v13, 0xffff0000, v109
	v_mul_f32_e32 v10, v134, v10
	v_mul_f32_e32 v11, v134, v11
	v_mul_f32_e32 v12, v134, v12
	v_mul_f32_e32 v13, v134, v13
	v_pk_mul_f32 v[10:11], v[2:3], v[10:11]
	v_pk_mul_f32 v[12:13], v[4:5], v[12:13]
	v_pk_add_f32 v[6:7], v[6:7], v[10:11]
	v_pk_add_f32 v[8:9], v[8:9], v[12:13]
	s_cmp_gt_u32 s37, 14
	s_cbranch_scc0 .Lpp_n14
	v_mov_b32_e32 v18, 0x3d888889
	v_pk_fma_f32 v[14:15], v[6:7], v[18:19], v[10:11] op_sel_hi:[1,0,1] neg_lo:[0,0,1] neg_hi:[0,0,1]
	v_pk_fma_f32 v[16:17], v[8:9], v[18:19], v[12:13] op_sel_hi:[1,0,1] neg_lo:[0,0,1] neg_hi:[0,0,1]
	v_cvt_pk_bf16_f32 v14, v14, v15
	v_cvt_pk_bf16_f32 v15, v16, v17
	global_store_dwordx2 v22, v[14:15], s[28:29]
	s_branch .Lpp_d14
.Lpp_n14:
	v_mov_b32_e32 v18, v27
	v_pk_fma_f32 v[14:15], v[6:7], v[18:19], v[10:11] op_sel_hi:[1,0,1] neg_lo:[0,0,1] neg_hi:[0,0,1]
	v_pk_fma_f32 v[16:17], v[8:9], v[18:19], v[12:13] op_sel_hi:[1,0,1] neg_lo:[0,0,1] neg_hi:[0,0,1]
	v_cvt_pk_bf16_f32 v14, v14, v15
	v_cvt_pk_bf16_f32 v15, v16, v17
	global_store_dwordx2 v22, v[14:15], s[28:29]
	v_lshlrev_b32_e32 v14, 16, v124
	v_and_b32_e32 v15, 0xffff0000, v124
	v_lshlrev_b32_e32 v16, 16, v125
	v_and_b32_e32 v17, 0xffff0000, v125
	v_mul_f32_e32 v14, v144, v14
	v_mul_f32_e32 v15, v144, v15
	v_mul_f32_e32 v16, v144, v16
	v_mul_f32_e32 v17, v144, v17
	v_pk_mul_f32 v[14:15], v[2:3], v[14:15]
	v_pk_mul_f32 v[16:17], v[4:5], v[16:17]
	v_pk_add_f32 v[6:7], v[6:7], v[14:15] neg_lo:[0,1] neg_hi:[0,1]
	v_pk_add_f32 v[8:9], v[8:9], v[16:17] neg_lo:[0,1] neg_hi:[0,1]
.Lpp_d14:
	s_add_u32 s28, s28, 0x480
	s_addc_u32 s29, s29, 0
	v_lshlrev_b32_e32 v10, 16, v110
	v_and_b32_e32 v11, 0xffff0000, v110
	v_lshlrev_b32_e32 v12, 16, v111
	v_and_b32_e32 v13, 0xffff0000, v111
	v_mul_f32_e32 v10, v135, v10
	v_mul_f32_e32 v11, v135, v11
	v_mul_f32_e32 v12, v135, v12
	v_mul_f32_e32 v13, v135, v13
	v_pk_mul_f32 v[10:11], v[2:3], v[10:11]
	v_pk_mul_f32 v[12:13], v[4:5], v[12:13]
	v_pk_add_f32 v[6:7], v[6:7], v[10:11]
	v_pk_add_f32 v[8:9], v[8:9], v[12:13]
	v_mov_b32_e32 v18, v27
	v_pk_fma_f32 v[14:15], v[6:7], v[18:19], v[10:11] op_sel_hi:[1,0,1] neg_lo:[0,0,1] neg_hi:[0,0,1]
	v_pk_fma_f32 v[16:17], v[8:9], v[18:19], v[12:13] op_sel_hi:[1,0,1] neg_lo:[0,0,1] neg_hi:[0,0,1]
	v_cvt_pk_bf16_f32 v14, v14, v15
	v_cvt_pk_bf16_f32 v15, v16, v17
	global_store_dwordx2 v22, v[14:15], s[28:29]
	v_lshlrev_b32_e32 v14, 16, v126
	v_and_b32_e32 v15, 0xffff0000, v126
	v_lshlrev_b32_e32 v16, 16, v127
	v_and_b32_e32 v17, 0xffff0000, v127
	v_mul_f32_e32 v14, v145, v14
	v_mul_f32_e32 v15, v145, v15
	v_mul_f32_e32 v16, v145, v16
	v_mul_f32_e32 v17, v145, v17
	v_pk_mul_f32 v[14:15], v[2:3], v[14:15]
	v_pk_mul_f32 v[16:17], v[4:5], v[16:17]
	v_pk_add_f32 v[6:7], v[6:7], v[14:15] neg_lo:[0,1] neg_hi:[0,1]
	v_pk_add_f32 v[8:9], v[8:9], v[16:17] neg_lo:[0,1] neg_hi:[0,1]
	s_add_u32 s28, s28, 0x480
	s_addc_u32 s29, s29, 0
	global_load_dwordx2 v[96:97], v20, s[24:25]
	s_add_u32 s24, s24, 0x1080
	s_addc_u32 s25, s25, 0
	global_load_dwordx2 v[98:99], v20, s[24:25]
	s_add_u32 s24, s24, 0x1080
	s_addc_u32 s25, s25, 0
	global_load_dwordx2 v[100:101], v20, s[24:25]
	s_add_u32 s24, s24, 0x1080
	s_addc_u32 s25, s25, 0
	global_load_dwordx2 v[102:103], v20, s[24:25]
	s_add_u32 s24, s24, 0x1080
	s_addc_u32 s25, s25, 0
	global_load_dwordx2 v[104:105], v20, s[24:25]
	s_add_u32 s24, s24, 0x1080
	s_addc_u32 s25, s25, 0
	global_load_dwordx2 v[106:107], v20, s[24:25]
	s_add_u32 s24, s24, 0x1080
	s_addc_u32 s25, s25, 0
	global_load_dwordx2 v[108:109], v20, s[24:25]
	s_add_u32 s24, s24, 0x1080
	s_addc_u32 s25, s25, 0
	global_load_dwordx2 v[110:111], v20, s[24:25]
	s_add_u32 s24, s24, 0x1080
	s_addc_u32 s25, s25, 0
	global_load_dwordx2 v[112:113], v20, s[26:27]
	s_add_u32 s26, s26, 0x1080
	s_addc_u32 s27, s27, 0
	global_load_dwordx2 v[114:115], v20, s[26:27]
	s_add_u32 s26, s26, 0x1080
	s_addc_u32 s27, s27, 0
	global_load_dwordx2 v[116:117], v20, s[26:27]
	s_add_u32 s26, s26, 0x1080
	s_addc_u32 s27, s27, 0
	global_load_dwordx2 v[118:119], v20, s[26:27]
	s_add_u32 s26, s26, 0x1080
	s_addc_u32 s27, s27, 0
	global_load_dwordx2 v[120:121], v20, s[26:27]
	s_add_u32 s26, s26, 0x1080
	s_addc_u32 s27, s27, 0
	global_load_dwordx2 v[122:123], v20, s[26:27]
	s_add_u32 s26, s26, 0x1080
	s_addc_u32 s27, s27, 0
	global_load_dwordx2 v[124:125], v20, s[26:27]
	s_add_u32 s26, s26, 0x1080
	s_addc_u32 s27, s27, 0
	global_load_dwordx2 v[126:127], v20, s[26:27]
	s_add_u32 s26, s26, 0x1080
	s_addc_u32 s27, s27, 0
	ds_read_b32 v128, v25 offset:156
	ds_read_b32 v129, v25 offset:160
	ds_read_b32 v130, v25 offset:164
	ds_read_b32 v131, v25 offset:168
	ds_read_b32 v132, v25 offset:172
	ds_read_b32 v133, v25 offset:176
	ds_read_b32 v134, v25 offset:180
	ds_read_b32 v135, v25 offset:184
	ds_read_b32 v136, v26 offset:96
	ds_read_b32 v137, v26 offset:100
	ds_read_b32 v138, v26 offset:104
	ds_read_b32 v139, v26 offset:108
	ds_read_b32 v142, v26 offset:112
	ds_read_b32 v143, v26 offset:116
	ds_read_b32 v144, v26 offset:120
	ds_read_b32 v145, v26 offset:124
	s_waitcnt vmcnt(24)
	s_waitcnt lgkmcnt(0)
	v_lshlrev_b32_e32 v10, 16, v64
	v_and_b32_e32 v11, 0xffff0000, v64
	v_lshlrev_b32_e32 v12, 16, v65
	v_and_b32_e32 v13, 0xffff0000, v65
	v_mul_f32_e32 v10, v146, v10
	v_mul_f32_e32 v11, v146, v11
	v_mul_f32_e32 v12, v146, v12
	v_mul_f32_e32 v13, v146, v13
	v_pk_mul_f32 v[10:11], v[2:3], v[10:11]
	v_pk_mul_f32 v[12:13], v[4:5], v[12:13]
	v_pk_add_f32 v[6:7], v[6:7], v[10:11]
	v_pk_add_f32 v[8:9], v[8:9], v[12:13]
	v_mov_b32_e32 v18, v27
	v_pk_fma_f32 v[14:15], v[6:7], v[18:19], v[10:11] op_sel_hi:[1,0,1] neg_lo:[0,0,1] neg_hi:[0,0,1]
	v_pk_fma_f32 v[16:17], v[8:9], v[18:19], v[12:13] op_sel_hi:[1,0,1] neg_lo:[0,0,1] neg_hi:[0,0,1]
	v_cvt_pk_bf16_f32 v14, v14, v15
	v_cvt_pk_bf16_f32 v15, v16, v17
	global_store_dwordx2 v22, v[14:15], s[28:29]
	v_lshlrev_b32_e32 v14, 16, v80
	v_and_b32_e32 v15, 0xffff0000, v80
	v_lshlrev_b32_e32 v16, 16, v81
	v_and_b32_e32 v17, 0xffff0000, v81
	v_mul_f32_e32 v14, v154, v14
	v_mul_f32_e32 v15, v154, v15
	v_mul_f32_e32 v16, v154, v16
	v_mul_f32_e32 v17, v154, v17
	v_pk_mul_f32 v[14:15], v[2:3], v[14:15]
	v_pk_mul_f32 v[16:17], v[4:5], v[16:17]
	v_pk_add_f32 v[6:7], v[6:7], v[14:15] neg_lo:[0,1] neg_hi:[0,1]
	v_pk_add_f32 v[8:9], v[8:9], v[16:17] neg_lo:[0,1] neg_hi:[0,1]
	s_add_u32 s28, s28, 0x480
	s_addc_u32 s29, s29, 0
	v_lshlrev_b32_e32 v10, 16, v66
	v_and_b32_e32 v11, 0xffff0000, v66
	v_lshlrev_b32_e32 v12, 16, v67
	v_and_b32_e32 v13, 0xffff0000, v67
	v_mul_f32_e32 v10, v147, v10
	v_mul_f32_e32 v11, v147, v11
	v_mul_f32_e32 v12, v147, v12
	v_mul_f32_e32 v13, v147, v13
	v_pk_mul_f32 v[10:11], v[2:3], v[10:11]
	v_pk_mul_f32 v[12:13], v[4:5], v[12:13]
	v_pk_add_f32 v[6:7], v[6:7], v[10:11]
	v_pk_add_f32 v[8:9], v[8:9], v[12:13]
	v_mov_b32_e32 v18, v27
	v_pk_fma_f32 v[14:15], v[6:7], v[18:19], v[10:11] op_sel_hi:[1,0,1] neg_lo:[0,0,1] neg_hi:[0,0,1]
	v_pk_fma_f32 v[16:17], v[8:9], v[18:19], v[12:13] op_sel_hi:[1,0,1] neg_lo:[0,0,1] neg_hi:[0,0,1]
	v_cvt_pk_bf16_f32 v14, v14, v15
	v_cvt_pk_bf16_f32 v15, v16, v17
	global_store_dwordx2 v22, v[14:15], s[28:29]
	s_cmp_eq_u32 s39, 1
	s_cbranch_scc0 .Lpp_q17
	global_store_dwordx4 v21, v[10:13], s[30:31]
	s_add_u32 s30, s30, 0x2000
	s_addc_u32 s31, s31, 0
.Lpp_q17:
	v_lshlrev_b32_e32 v14, 16, v82
	v_and_b32_e32 v15, 0xffff0000, v82
	v_lshlrev_b32_e32 v16, 16, v83
	v_and_b32_e32 v17, 0xffff0000, v83
	v_mul_f32_e32 v14, v155, v14
	v_mul_f32_e32 v15, v155, v15
	v_mul_f32_e32 v16, v155, v16
	v_mul_f32_e32 v17, v155, v17
	v_pk_mul_f32 v[14:15], v[2:3], v[14:15]
	v_pk_mul_f32 v[16:17], v[4:5], v[16:17]
	v_pk_add_f32 v[6:7], v[6:7], v[14:15] neg_lo:[0,1] neg_hi:[0,1]
	v_pk_add_f32 v[8:9], v[8:9], v[16:17] neg_lo:[0,1] neg_hi:[0,1]
	s_add_u32 s28, s28, 0x480
	s_addc_u32 s29, s29, 0
	v_lshlrev_b32_e32 v10, 16, v68
	v_and_b32_e32 v11, 0xffff0000, v68
	v_lshlrev_b32_e32 v12, 16, v69
	v_and_b32_e32 v13, 0xffff0000, v69
	v_mul_f32_e32 v10, v148, v10
	v_mul_f32_e32 v11, v148, v11
	v_mul_f32_e32 v12, v148, v12
	v_mul_f32_e32 v13, v148, v13
	v_pk_mul_f32 v[10:11], v[2:3], v[10:11]
	v_pk_mul_f32 v[12:13], v[4:5], v[12:13]
	v_pk_add_f32 v[6:7], v[6:7], v[10:11]
	v_pk_add_f32 v[8:9], v[8:9], v[12:13]
	v_mov_b32_e32 v18, v27
	v_pk_fma_f32 v[14:15], v[6:7], v[18:19], v[10:11] op_sel_hi:[1,0,1] neg_lo:[0,0,1] neg_hi:[0,0,1]
	v_pk_fma_f32 v[16:17], v[8:9], v[18:19], v[12:13] op_sel_hi:[1,0,1] neg_lo:[0,0,1] neg_hi:[0,0,1]
	v_cvt_pk_bf16_f32 v14, v14, v15
	v_cvt_pk_bf16_f32 v15, v16, v17
	global_store_dwordx2 v22, v[14:15], s[28:29]
	s_cmp_eq_u32 s39, 1
	s_cbranch_scc0 .Lpp_q18
	global_store_dwordx4 v21, v[10:13], s[30:31]
	s_add_u32 s30, s30, 0x2000
	s_addc_u32 s31, s31, 0
.Lpp_q18:
	v_lshlrev_b32_e32 v14, 16, v84
	v_and_b32_e32 v15, 0xffff0000, v84
	v_lshlrev_b32_e32 v16, 16, v85
	v_and_b32_e32 v17, 0xffff0000, v85
	v_mul_f32_e32 v14, v156, v14
	v_mul_f32_e32 v15, v156, v15
	v_mul_f32_e32 v16, v156, v16
	v_mul_f32_e32 v17, v156, v17
	v_pk_mul_f32 v[14:15], v[2:3], v[14:15]
	v_pk_mul_f32 v[16:17], v[4:5], v[16:17]
	v_pk_add_f32 v[6:7], v[6:7], v[14:15] neg_lo:[0,1] neg_hi:[0,1]
	v_pk_add_f32 v[8:9], v[8:9], v[16:17] neg_lo:[0,1] neg_hi:[0,1]
	s_add_u32 s28, s28, 0x480
	s_addc_u32 s29, s29, 0
	v_lshlrev_b32_e32 v10, 16, v70
	v_and_b32_e32 v11, 0xffff0000, v70
	v_lshlrev_b32_e32 v12, 16, v71
	v_and_b32_e32 v13, 0xffff0000, v71
	v_mul_f32_e32 v10, v149, v10
	v_mul_f32_e32 v11, v149, v11
	v_mul_f32_e32 v12, v149, v12
	v_mul_f32_e32 v13, v149, v13
	v_pk_mul_f32 v[10:11], v[2:3], v[10:11]
	v_pk_mul_f32 v[12:13], v[4:5], v[12:13]
	v_pk_add_f32 v[6:7], v[6:7], v[10:11]
	v_pk_add_f32 v[8:9], v[8:9], v[12:13]
	v_mov_b32_e32 v18, v27
	v_pk_fma_f32 v[14:15], v[6:7], v[18:19], v[10:11] op_sel_hi:[1,0,1] neg_lo:[0,0,1] neg_hi:[0,0,1]
	v_pk_fma_f32 v[16:17], v[8:9], v[18:19], v[12:13] op_sel_hi:[1,0,1] neg_lo:[0,0,1] neg_hi:[0,0,1]
	v_cvt_pk_bf16_f32 v14, v14, v15
	v_cvt_pk_bf16_f32 v15, v16, v17
	global_store_dwordx2 v22, v[14:15], s[28:29]
	s_cmp_eq_u32 s39, 1
	s_cbranch_scc0 .Lpp_q19
	global_store_dwordx4 v21, v[10:13], s[30:31]
	s_add_u32 s30, s30, 0x2000
	s_addc_u32 s31, s31, 0
.Lpp_q19:
	v_lshlrev_b32_e32 v14, 16, v86
	v_and_b32_e32 v15, 0xffff0000, v86
	v_lshlrev_b32_e32 v16, 16, v87
	v_and_b32_e32 v17, 0xffff0000, v87
	v_mul_f32_e32 v14, v157, v14
	v_mul_f32_e32 v15, v157, v15
	v_mul_f32_e32 v16, v157, v16
	v_mul_f32_e32 v17, v157, v17
	v_pk_mul_f32 v[14:15], v[2:3], v[14:15]
	v_pk_mul_f32 v[16:17], v[4:5], v[16:17]
	v_pk_add_f32 v[6:7], v[6:7], v[14:15] neg_lo:[0,1] neg_hi:[0,1]
	v_pk_add_f32 v[8:9], v[8:9], v[16:17] neg_lo:[0,1] neg_hi:[0,1]
	s_add_u32 s28, s28, 0x480
	s_addc_u32 s29, s29, 0
	v_lshlrev_b32_e32 v10, 16, v72
	v_and_b32_e32 v11, 0xffff0000, v72
	v_lshlrev_b32_e32 v12, 16, v73
	v_and_b32_e32 v13, 0xffff0000, v73
	v_mul_f32_e32 v10, v150, v10
	v_mul_f32_e32 v11, v150, v11
	v_mul_f32_e32 v12, v150, v12
	v_mul_f32_e32 v13, v150, v13
	v_pk_mul_f32 v[10:11], v[2:3], v[10:11]
	v_pk_mul_f32 v[12:13], v[4:5], v[12:13]
	v_pk_add_f32 v[6:7], v[6:7], v[10:11]
	v_pk_add_f32 v[8:9], v[8:9], v[12:13]
	v_mov_b32_e32 v18, v27
	v_pk_fma_f32 v[14:15], v[6:7], v[18:19], v[10:11] op_sel_hi:[1,0,1] neg_lo:[0,0,1] neg_hi:[0,0,1]
	v_pk_fma_f32 v[16:17], v[8:9], v[18:19], v[12:13] op_sel_hi:[1,0,1] neg_lo:[0,0,1] neg_hi:[0,0,1]
	v_cvt_pk_bf16_f32 v14, v14, v15
	v_cvt_pk_bf16_f32 v15, v16, v17
	global_store_dwordx2 v22, v[14:15], s[28:29]
	s_cmp_eq_u32 s39, 1
	s_cbranch_scc0 .Lpp_q20
	global_store_dwordx4 v21, v[10:13], s[30:31]
	s_add_u32 s30, s30, 0x2000
	s_addc_u32 s31, s31, 0
.Lpp_q20:
	v_lshlrev_b32_e32 v14, 16, v88
	v_and_b32_e32 v15, 0xffff0000, v88
	v_lshlrev_b32_e32 v16, 16, v89
	v_and_b32_e32 v17, 0xffff0000, v89
	v_mul_f32_e32 v14, v158, v14
	v_mul_f32_e32 v15, v158, v15
	v_mul_f32_e32 v16, v158, v16
	v_mul_f32_e32 v17, v158, v17
	v_pk_mul_f32 v[14:15], v[2:3], v[14:15]
	v_pk_mul_f32 v[16:17], v[4:5], v[16:17]
	v_pk_add_f32 v[6:7], v[6:7], v[14:15] neg_lo:[0,1] neg_hi:[0,1]
	v_pk_add_f32 v[8:9], v[8:9], v[16:17] neg_lo:[0,1] neg_hi:[0,1]
	s_add_u32 s28, s28, 0x480
	s_addc_u32 s29, s29, 0
	v_lshlrev_b32_e32 v10, 16, v74
	v_and_b32_e32 v11, 0xffff0000, v74
	v_lshlrev_b32_e32 v12, 16, v75
	v_and_b32_e32 v13, 0xffff0000, v75
	v_mul_f32_e32 v10, v151, v10
	v_mul_f32_e32 v11, v151, v11
	v_mul_f32_e32 v12, v151, v12
	v_mul_f32_e32 v13, v151, v13
	v_pk_mul_f32 v[10:11], v[2:3], v[10:11]
	v_pk_mul_f32 v[12:13], v[4:5], v[12:13]
	v_pk_add_f32 v[6:7], v[6:7], v[10:11]
	v_pk_add_f32 v[8:9], v[8:9], v[12:13]
	v_mov_b32_e32 v18, v27
	v_pk_fma_f32 v[14:15], v[6:7], v[18:19], v[10:11] op_sel_hi:[1,0,1] neg_lo:[0,0,1] neg_hi:[0,0,1]
	v_pk_fma_f32 v[16:17], v[8:9], v[18:19], v[12:13] op_sel_hi:[1,0,1] neg_lo:[0,0,1] neg_hi:[0,0,1]
	v_cvt_pk_bf16_f32 v14, v14, v15
	v_cvt_pk_bf16_f32 v15, v16, v17
	global_store_dwordx2 v22, v[14:15], s[28:29]
	s_cmp_eq_u32 s39, 1
	s_cbranch_scc0 .Lpp_q21
	global_store_dwordx4 v21, v[10:13], s[30:31]
	s_add_u32 s30, s30, 0x2000
	s_addc_u32 s31, s31, 0
.Lpp_q21:
	v_lshlrev_b32_e32 v14, 16, v90
	v_and_b32_e32 v15, 0xffff0000, v90
	v_lshlrev_b32_e32 v16, 16, v91
	v_and_b32_e32 v17, 0xffff0000, v91
	v_mul_f32_e32 v14, v159, v14
	v_mul_f32_e32 v15, v159, v15
	v_mul_f32_e32 v16, v159, v16
	v_mul_f32_e32 v17, v159, v17
	v_pk_mul_f32 v[14:15], v[2:3], v[14:15]
	v_pk_mul_f32 v[16:17], v[4:5], v[16:17]
	v_pk_add_f32 v[6:7], v[6:7], v[14:15] neg_lo:[0,1] neg_hi:[0,1]
	v_pk_add_f32 v[8:9], v[8:9], v[16:17] neg_lo:[0,1] neg_hi:[0,1]
	s_add_u32 s28, s28, 0x480
	s_addc_u32 s29, s29, 0
	v_lshlrev_b32_e32 v10, 16, v76
	v_and_b32_e32 v11, 0xffff0000, v76
	v_lshlrev_b32_e32 v12, 16, v77
	v_and_b32_e32 v13, 0xffff0000, v77
	v_mul_f32_e32 v10, v152, v10
	v_mul_f32_e32 v11, v152, v11
	v_mul_f32_e32 v12, v152, v12
	v_mul_f32_e32 v13, v152, v13
	v_pk_mul_f32 v[10:11], v[2:3], v[10:11]
	v_pk_mul_f32 v[12:13], v[4:5], v[12:13]
	v_pk_add_f32 v[6:7], v[6:7], v[10:11]
	v_pk_add_f32 v[8:9], v[8:9], v[12:13]
	v_mov_b32_e32 v18, v27
	v_pk_fma_f32 v[14:15], v[6:7], v[18:19], v[10:11] op_sel_hi:[1,0,1] neg_lo:[0,0,1] neg_hi:[0,0,1]
	v_pk_fma_f32 v[16:17], v[8:9], v[18:19], v[12:13] op_sel_hi:[1,0,1] neg_lo:[0,0,1] neg_hi:[0,0,1]
	v_cvt_pk_bf16_f32 v14, v14, v15
	v_cvt_pk_bf16_f32 v15, v16, v17
	global_store_dwordx2 v22, v[14:15], s[28:29]
	s_cmp_eq_u32 s39, 1
	s_cbranch_scc0 .Lpp_q22
	global_store_dwordx4 v21, v[10:13], s[30:31]
	s_add_u32 s30, s30, 0x2000
	s_addc_u32 s31, s31, 0
.Lpp_q22:
	v_lshlrev_b32_e32 v14, 16, v92
	v_and_b32_e32 v15, 0xffff0000, v92
	v_lshlrev_b32_e32 v16, 16, v93
	v_and_b32_e32 v17, 0xffff0000, v93
	v_mul_f32_e32 v14, v160, v14
	v_mul_f32_e32 v15, v160, v15
	v_mul_f32_e32 v16, v160, v16
	v_mul_f32_e32 v17, v160, v17
	v_pk_mul_f32 v[14:15], v[2:3], v[14:15]
	v_pk_mul_f32 v[16:17], v[4:5], v[16:17]
	v_pk_add_f32 v[6:7], v[6:7], v[14:15] neg_lo:[0,1] neg_hi:[0,1]
	v_pk_add_f32 v[8:9], v[8:9], v[16:17] neg_lo:[0,1] neg_hi:[0,1]
	s_add_u32 s28, s28, 0x480
	s_addc_u32 s29, s29, 0
	v_lshlrev_b32_e32 v10, 16, v78
	v_and_b32_e32 v11, 0xffff0000, v78
	v_lshlrev_b32_e32 v12, 16, v79
	v_and_b32_e32 v13, 0xffff0000, v79
	v_mul_f32_e32 v10, v153, v10
	v_mul_f32_e32 v11, v153, v11
	v_mul_f32_e32 v12, v153, v12
	v_mul_f32_e32 v13, v153, v13
	v_pk_mul_f32 v[10:11], v[2:3], v[10:11]
	v_pk_mul_f32 v[12:13], v[4:5], v[12:13]
	v_pk_add_f32 v[6:7], v[6:7], v[10:11]
	v_pk_add_f32 v[8:9], v[8:9], v[12:13]
	v_mov_b32_e32 v18, v27
	v_pk_fma_f32 v[14:15], v[6:7], v[18:19], v[10:11] op_sel_hi:[1,0,1] neg_lo:[0,0,1] neg_hi:[0,0,1]
	v_pk_fma_f32 v[16:17], v[8:9], v[18:19], v[12:13] op_sel_hi:[1,0,1] neg_lo:[0,0,1] neg_hi:[0,0,1]
	v_cvt_pk_bf16_f32 v14, v14, v15
	v_cvt_pk_bf16_f32 v15, v16, v17
	global_store_dwordx2 v22, v[14:15], s[28:29]
	s_cmp_eq_u32 s39, 1
	s_cbranch_scc0 .Lpp_q23
	global_store_dwordx4 v21, v[10:13], s[30:31]
	s_add_u32 s30, s30, 0x2000
	s_addc_u32 s31, s31, 0
.Lpp_q23:
	v_lshlrev_b32_e32 v14, 16, v94
	v_and_b32_e32 v15, 0xffff0000, v94
	v_lshlrev_b32_e32 v16, 16, v95
	v_and_b32_e32 v17, 0xffff0000, v95
	v_mul_f32_e32 v14, v162, v14
	v_mul_f32_e32 v15, v162, v15
	v_mul_f32_e32 v16, v162, v16
	v_mul_f32_e32 v17, v162, v17
	v_pk_mul_f32 v[14:15], v[2:3], v[14:15]
	v_pk_mul_f32 v[16:17], v[4:5], v[16:17]
	v_pk_add_f32 v[6:7], v[6:7], v[14:15] neg_lo:[0,1] neg_hi:[0,1]
	v_pk_add_f32 v[8:9], v[8:9], v[16:17] neg_lo:[0,1] neg_hi:[0,1]
	s_add_u32 s28, s28, 0x480
	s_addc_u32 s29, s29, 0
	s_waitcnt vmcnt(8)
	s_waitcnt lgkmcnt(0)
	v_lshlrev_b32_e32 v10, 16, v96
	v_and_b32_e32 v11, 0xffff0000, v96
	v_lshlrev_b32_e32 v12, 16, v97
	v_and_b32_e32 v13, 0xffff0000, v97
	v_mul_f32_e32 v10, v128, v10
	v_mul_f32_e32 v11, v128, v11
	v_mul_f32_e32 v12, v128, v12
	v_mul_f32_e32 v13, v128, v13
	v_pk_mul_f32 v[10:11], v[2:3], v[10:11]
	v_pk_mul_f32 v[12:13], v[4:5], v[12:13]
	v_pk_add_f32 v[6:7], v[6:7], v[10:11]
	v_pk_add_f32 v[8:9], v[8:9], v[12:13]
	v_mov_b32_e32 v18, v27
	v_pk_fma_f32 v[14:15], v[6:7], v[18:19], v[10:11] op_sel_hi:[1,0,1] neg_lo:[0,0,1] neg_hi:[0,0,1]
	v_pk_fma_f32 v[16:17], v[8:9], v[18:19], v[12:13] op_sel_hi:[1,0,1] neg_lo:[0,0,1] neg_hi:[0,0,1]
	v_cvt_pk_bf16_f32 v14, v14, v15
	v_cvt_pk_bf16_f32 v15, v16, v17
	global_store_dwordx2 v22, v[14:15], s[28:29]
	s_cmp_eq_u32 s39, 1
	s_cbranch_scc0 .Lpp_q24
	global_store_dwordx4 v21, v[10:13], s[30:31]
	s_add_u32 s30, s30, 0x2000
	s_addc_u32 s31, s31, 0
.Lpp_q24:
	v_lshlrev_b32_e32 v14, 16, v112
	v_and_b32_e32 v15, 0xffff0000, v112
	v_lshlrev_b32_e32 v16, 16, v113
	v_and_b32_e32 v17, 0xffff0000, v113
	v_mul_f32_e32 v14, v136, v14
	v_mul_f32_e32 v15, v136, v15
	v_mul_f32_e32 v16, v136, v16
	v_mul_f32_e32 v17, v136, v17
	v_pk_mul_f32 v[14:15], v[2:3], v[14:15]
	v_pk_mul_f32 v[16:17], v[4:5], v[16:17]
	v_pk_add_f32 v[6:7], v[6:7], v[14:15] neg_lo:[0,1] neg_hi:[0,1]
	v_pk_add_f32 v[8:9], v[8:9], v[16:17] neg_lo:[0,1] neg_hi:[0,1]
	s_add_u32 s28, s28, 0x480
	s_addc_u32 s29, s29, 0
	v_lshlrev_b32_e32 v10, 16, v98
	v_and_b32_e32 v11, 0xffff0000, v98
	v_lshlrev_b32_e32 v12, 16, v99
	v_and_b32_e32 v13, 0xffff0000, v99
	v_mul_f32_e32 v10, v129, v10
	v_mul_f32_e32 v11, v129, v11
	v_mul_f32_e32 v12, v129, v12
	v_mul_f32_e32 v13, v129, v13
	v_pk_mul_f32 v[10:11], v[2:3], v[10:11]
	v_pk_mul_f32 v[12:13], v[4:5], v[12:13]
	v_pk_add_f32 v[6:7], v[6:7], v[10:11]
	v_pk_add_f32 v[8:9], v[8:9], v[12:13]
	v_mov_b32_e32 v18, v27
	v_pk_fma_f32 v[14:15], v[6:7], v[18:19], v[10:11] op_sel_hi:[1,0,1] neg_lo:[0,0,1] neg_hi:[0,0,1]
	v_pk_fma_f32 v[16:17], v[8:9], v[18:19], v[12:13] op_sel_hi:[1,0,1] neg_lo:[0,0,1] neg_hi:[0,0,1]
	v_cvt_pk_bf16_f32 v14, v14, v15
	v_cvt_pk_bf16_f32 v15, v16, v17
	global_store_dwordx2 v22, v[14:15], s[28:29]
	s_cmp_eq_u32 s39, 1
	s_cbranch_scc0 .Lpp_q25
	global_store_dwordx4 v21, v[10:13], s[30:31]
	s_add_u32 s30, s30, 0x2000
	s_addc_u32 s31, s31, 0
.Lpp_q25:
	v_lshlrev_b32_e32 v14, 16, v114
	v_and_b32_e32 v15, 0xffff0000, v114
	v_lshlrev_b32_e32 v16, 16, v115
	v_and_b32_e32 v17, 0xffff0000, v115
	v_mul_f32_e32 v14, v137, v14
	v_mul_f32_e32 v15, v137, v15
	v_mul_f32_e32 v16, v137, v16
	v_mul_f32_e32 v17, v137, v17
	v_pk_mul_f32 v[14:15], v[2:3], v[14:15]
	v_pk_mul_f32 v[16:17], v[4:5], v[16:17]
	v_pk_add_f32 v[6:7], v[6:7], v[14:15] neg_lo:[0,1] neg_hi:[0,1]
	v_pk_add_f32 v[8:9], v[8:9], v[16:17] neg_lo:[0,1] neg_hi:[0,1]
	s_add_u32 s28, s28, 0x480
	s_addc_u32 s29, s29, 0
	v_lshlrev_b32_e32 v10, 16, v100
	v_and_b32_e32 v11, 0xffff0000, v100
	v_lshlrev_b32_e32 v12, 16, v101
	v_and_b32_e32 v13, 0xffff0000, v101
	v_mul_f32_e32 v10, v130, v10
	v_mul_f32_e32 v11, v130, v11
	v_mul_f32_e32 v12, v130, v12
	v_mul_f32_e32 v13, v130, v13
	v_pk_mul_f32 v[10:11], v[2:3], v[10:11]
	v_pk_mul_f32 v[12:13], v[4:5], v[12:13]
	v_pk_add_f32 v[6:7], v[6:7], v[10:11]
	v_pk_add_f32 v[8:9], v[8:9], v[12:13]
	v_mov_b32_e32 v18, v27
	v_pk_fma_f32 v[14:15], v[6:7], v[18:19], v[10:11] op_sel_hi:[1,0,1] neg_lo:[0,0,1] neg_hi:[0,0,1]
	v_pk_fma_f32 v[16:17], v[8:9], v[18:19], v[12:13] op_sel_hi:[1,0,1] neg_lo:[0,0,1] neg_hi:[0,0,1]
	v_cvt_pk_bf16_f32 v14, v14, v15
	v_cvt_pk_bf16_f32 v15, v16, v17
	global_store_dwordx2 v22, v[14:15], s[28:29]
	s_cmp_eq_u32 s39, 1
	s_cbranch_scc0 .Lpp_q26
	global_store_dwordx4 v21, v[10:13], s[30:31]
	s_add_u32 s30, s30, 0x2000
	s_addc_u32 s31, s31, 0
.Lpp_q26:
	v_lshlrev_b32_e32 v14, 16, v116
	v_and_b32_e32 v15, 0xffff0000, v116
	v_lshlrev_b32_e32 v16, 16, v117
	v_and_b32_e32 v17, 0xffff0000, v117
	v_mul_f32_e32 v14, v138, v14
	v_mul_f32_e32 v15, v138, v15
	v_mul_f32_e32 v16, v138, v16
	v_mul_f32_e32 v17, v138, v17
	v_pk_mul_f32 v[14:15], v[2:3], v[14:15]
	v_pk_mul_f32 v[16:17], v[4:5], v[16:17]
	v_pk_add_f32 v[6:7], v[6:7], v[14:15] neg_lo:[0,1] neg_hi:[0,1]
	v_pk_add_f32 v[8:9], v[8:9], v[16:17] neg_lo:[0,1] neg_hi:[0,1]
	s_add_u32 s28, s28, 0x480
	s_addc_u32 s29, s29, 0
	v_lshlrev_b32_e32 v10, 16, v102
	v_and_b32_e32 v11, 0xffff0000, v102
	v_lshlrev_b32_e32 v12, 16, v103
	v_and_b32_e32 v13, 0xffff0000, v103
	v_mul_f32_e32 v10, v131, v10
	v_mul_f32_e32 v11, v131, v11
	v_mul_f32_e32 v12, v131, v12
	v_mul_f32_e32 v13, v131, v13
	v_pk_mul_f32 v[10:11], v[2:3], v[10:11]
	v_pk_mul_f32 v[12:13], v[4:5], v[12:13]
	v_pk_add_f32 v[6:7], v[6:7], v[10:11]
	v_pk_add_f32 v[8:9], v[8:9], v[12:13]
	v_mov_b32_e32 v18, v27
	v_pk_fma_f32 v[14:15], v[6:7], v[18:19], v[10:11] op_sel_hi:[1,0,1] neg_lo:[0,0,1] neg_hi:[0,0,1]
	v_pk_fma_f32 v[16:17], v[8:9], v[18:19], v[12:13] op_sel_hi:[1,0,1] neg_lo:[0,0,1] neg_hi:[0,0,1]
	v_cvt_pk_bf16_f32 v14, v14, v15
	v_cvt_pk_bf16_f32 v15, v16, v17
	global_store_dwordx2 v22, v[14:15], s[28:29]
	s_cmp_eq_u32 s39, 1
	s_cbranch_scc0 .Lpp_q27
	global_store_dwordx4 v21, v[10:13], s[30:31]
	s_add_u32 s30, s30, 0x2000
	s_addc_u32 s31, s31, 0
.Lpp_q27:
	v_lshlrev_b32_e32 v14, 16, v118
	v_and_b32_e32 v15, 0xffff0000, v118
	v_lshlrev_b32_e32 v16, 16, v119
	v_and_b32_e32 v17, 0xffff0000, v119
	v_mul_f32_e32 v14, v139, v14
	v_mul_f32_e32 v15, v139, v15
	v_mul_f32_e32 v16, v139, v16
	v_mul_f32_e32 v17, v139, v17
	v_pk_mul_f32 v[14:15], v[2:3], v[14:15]
	v_pk_mul_f32 v[16:17], v[4:5], v[16:17]
	v_pk_add_f32 v[6:7], v[6:7], v[14:15] neg_lo:[0,1] neg_hi:[0,1]
	v_pk_add_f32 v[8:9], v[8:9], v[16:17] neg_lo:[0,1] neg_hi:[0,1]
	s_add_u32 s28, s28, 0x480
	s_addc_u32 s29, s29, 0
	v_lshlrev_b32_e32 v10, 16, v104
	v_and_b32_e32 v11, 0xffff0000, v104
	v_lshlrev_b32_e32 v12, 16, v105
	v_and_b32_e32 v13, 0xffff0000, v105
	v_mul_f32_e32 v10, v132, v10
	v_mul_f32_e32 v11, v132, v11
	v_mul_f32_e32 v12, v132, v12
	v_mul_f32_e32 v13, v132, v13
	v_pk_mul_f32 v[10:11], v[2:3], v[10:11]
	v_pk_mul_f32 v[12:13], v[4:5], v[12:13]
	v_pk_add_f32 v[6:7], v[6:7], v[10:11]
	v_pk_add_f32 v[8:9], v[8:9], v[12:13]
	v_mov_b32_e32 v18, v27
	v_pk_fma_f32 v[14:15], v[6:7], v[18:19], v[10:11] op_sel_hi:[1,0,1] neg_lo:[0,0,1] neg_hi:[0,0,1]
	v_pk_fma_f32 v[16:17], v[8:9], v[18:19], v[12:13] op_sel_hi:[1,0,1] neg_lo:[0,0,1] neg_hi:[0,0,1]
	v_cvt_pk_bf16_f32 v14, v14, v15
	v_cvt_pk_bf16_f32 v15, v16, v17
	global_store_dwordx2 v22, v[14:15], s[28:29]
	s_cmp_eq_u32 s39, 1
	s_cbranch_scc0 .Lpp_q28
	global_store_dwordx4 v21, v[10:13], s[30:31]
	s_add_u32 s30, s30, 0x2000
	s_addc_u32 s31, s31, 0
.Lpp_q28:
	v_lshlrev_b32_e32 v14, 16, v120
	v_and_b32_e32 v15, 0xffff0000, v120
	v_lshlrev_b32_e32 v16, 16, v121
	v_and_b32_e32 v17, 0xffff0000, v121
	v_mul_f32_e32 v14, v142, v14
	v_mul_f32_e32 v15, v142, v15
	v_mul_f32_e32 v16, v142, v16
	v_mul_f32_e32 v17, v142, v17
	v_pk_mul_f32 v[14:15], v[2:3], v[14:15]
	v_pk_mul_f32 v[16:17], v[4:5], v[16:17]
	v_pk_add_f32 v[6:7], v[6:7], v[14:15] neg_lo:[0,1] neg_hi:[0,1]
	v_pk_add_f32 v[8:9], v[8:9], v[16:17] neg_lo:[0,1] neg_hi:[0,1]
	s_add_u32 s28, s28, 0x480
	s_addc_u32 s29, s29, 0
	v_lshlrev_b32_e32 v10, 16, v106
	v_and_b32_e32 v11, 0xffff0000, v106
	v_lshlrev_b32_e32 v12, 16, v107
	v_and_b32_e32 v13, 0xffff0000, v107
	v_mul_f32_e32 v10, v133, v10
	v_mul_f32_e32 v11, v133, v11
	v_mul_f32_e32 v12, v133, v12
	v_mul_f32_e32 v13, v133, v13
	v_pk_mul_f32 v[10:11], v[2:3], v[10:11]
	v_pk_mul_f32 v[12:13], v[4:5], v[12:13]
	v_pk_add_f32 v[6:7], v[6:7], v[10:11]
	v_pk_add_f32 v[8:9], v[8:9], v[12:13]
	v_mov_b32_e32 v18, v27
	v_pk_fma_f32 v[14:15], v[6:7], v[18:19], v[10:11] op_sel_hi:[1,0,1] neg_lo:[0,0,1] neg_hi:[0,0,1]
	v_pk_fma_f32 v[16:17], v[8:9], v[18:19], v[12:13] op_sel_hi:[1,0,1] neg_lo:[0,0,1] neg_hi:[0,0,1]
	v_cvt_pk_bf16_f32 v14, v14, v15
	v_cvt_pk_bf16_f32 v15, v16, v17
	global_store_dwordx2 v22, v[14:15], s[28:29]
	s_cmp_eq_u32 s39, 1
	s_cbranch_scc0 .Lpp_q29
	global_store_dwordx4 v21, v[10:13], s[30:31]
	s_add_u32 s30, s30, 0x2000
	s_addc_u32 s31, s31, 0
.Lpp_q29:
	v_lshlrev_b32_e32 v14, 16, v122
	v_and_b32_e32 v15, 0xffff0000, v122
	v_lshlrev_b32_e32 v16, 16, v123
	v_and_b32_e32 v17, 0xffff0000, v123
	v_mul_f32_e32 v14, v143, v14
	v_mul_f32_e32 v15, v143, v15
	v_mul_f32_e32 v16, v143, v16
	v_mul_f32_e32 v17, v143, v17
	v_pk_mul_f32 v[14:15], v[2:3], v[14:15]
	v_pk_mul_f32 v[16:17], v[4:5], v[16:17]
	v_pk_add_f32 v[6:7], v[6:7], v[14:15] neg_lo:[0,1] neg_hi:[0,1]
	v_pk_add_f32 v[8:9], v[8:9], v[16:17] neg_lo:[0,1] neg_hi:[0,1]
	s_add_u32 s28, s28, 0x480
	s_addc_u32 s29, s29, 0
	v_lshlrev_b32_e32 v10, 16, v108
	v_and_b32_e32 v11, 0xffff0000, v108
	v_lshlrev_b32_e32 v12, 16, v109
	v_and_b32_e32 v13, 0xffff0000, v109
	v_mul_f32_e32 v10, v134, v10
	v_mul_f32_e32 v11, v134, v11
	v_mul_f32_e32 v12, v134, v12
	v_mul_f32_e32 v13, v134, v13
	v_pk_mul_f32 v[10:11], v[2:3], v[10:11]
	v_pk_mul_f32 v[12:13], v[4:5], v[12:13]
	v_pk_add_f32 v[6:7], v[6:7], v[10:11]
	v_pk_add_f32 v[8:9], v[8:9], v[12:13]
	v_mov_b32_e32 v18, v27
	v_pk_fma_f32 v[14:15], v[6:7], v[18:19], v[10:11] op_sel_hi:[1,0,1] neg_lo:[0,0,1] neg_hi:[0,0,1]
	v_pk_fma_f32 v[16:17], v[8:9], v[18:19], v[12:13] op_sel_hi:[1,0,1] neg_lo:[0,0,1] neg_hi:[0,0,1]
	v_cvt_pk_bf16_f32 v14, v14, v15
	v_cvt_pk_bf16_f32 v15, v16, v17
	global_store_dwordx2 v22, v[14:15], s[28:29]
	s_cmp_eq_u32 s39, 1
	s_cbranch_scc0 .Lpp_q30
	global_store_dwordx4 v21, v[10:13], s[30:31]
	s_add_u32 s30, s30, 0x2000
	s_addc_u32 s31, s31, 0
.Lpp_q30:
	v_lshlrev_b32_e32 v14, 16, v124
	v_and_b32_e32 v15, 0xffff0000, v124
	v_lshlrev_b32_e32 v16, 16, v125
	v_and_b32_e32 v17, 0xffff0000, v125
	v_mul_f32_e32 v14, v144, v14
	v_mul_f32_e32 v15, v144, v15
	v_mul_f32_e32 v16, v144, v16
	v_mul_f32_e32 v17, v144, v17
	v_pk_mul_f32 v[14:15], v[2:3], v[14:15]
	v_pk_mul_f32 v[16:17], v[4:5], v[16:17]
	v_pk_add_f32 v[6:7], v[6:7], v[14:15] neg_lo:[0,1] neg_hi:[0,1]
	v_pk_add_f32 v[8:9], v[8:9], v[16:17] neg_lo:[0,1] neg_hi:[0,1]
	s_add_u32 s28, s28, 0x480
	s_addc_u32 s29, s29, 0
	v_lshlrev_b32_e32 v10, 16, v110
	v_and_b32_e32 v11, 0xffff0000, v110
	v_lshlrev_b32_e32 v12, 16, v111
	v_and_b32_e32 v13, 0xffff0000, v111
	v_mul_f32_e32 v10, v135, v10
	v_mul_f32_e32 v11, v135, v11
	v_mul_f32_e32 v12, v135, v12
	v_mul_f32_e32 v13, v135, v13
	v_pk_mul_f32 v[10:11], v[2:3], v[10:11]
	v_pk_mul_f32 v[12:13], v[4:5], v[12:13]
	v_pk_add_f32 v[6:7], v[6:7], v[10:11]
	v_pk_add_f32 v[8:9], v[8:9], v[12:13]
	v_mov_b32_e32 v18, v27
	v_pk_fma_f32 v[14:15], v[6:7], v[18:19], v[10:11] op_sel_hi:[1,0,1] neg_lo:[0,0,1] neg_hi:[0,0,1]
	v_pk_fma_f32 v[16:17], v[8:9], v[18:19], v[12:13] op_sel_hi:[1,0,1] neg_lo:[0,0,1] neg_hi:[0,0,1]
	v_cvt_pk_bf16_f32 v14, v14, v15
	v_cvt_pk_bf16_f32 v15, v16, v17
	global_store_dwordx2 v22, v[14:15], s[28:29]
	s_cmp_eq_u32 s39, 1
	s_cbranch_scc0 .Lpp_q31
	global_store_dwordx4 v21, v[10:13], s[30:31]
	s_add_u32 s30, s30, 0x2000
	s_addc_u32 s31, s31, 0
.Lpp_q31:
	v_lshlrev_b32_e32 v14, 16, v126
	v_and_b32_e32 v15, 0xffff0000, v126
	v_lshlrev_b32_e32 v16, 16, v127
	v_and_b32_e32 v17, 0xffff0000, v127
	v_mul_f32_e32 v14, v145, v14
	v_mul_f32_e32 v15, v145, v15
	v_mul_f32_e32 v16, v145, v16
	v_mul_f32_e32 v17, v145, v17
	v_pk_mul_f32 v[14:15], v[2:3], v[14:15]
	v_pk_mul_f32 v[16:17], v[4:5], v[16:17]
	v_pk_add_f32 v[6:7], v[6:7], v[14:15] neg_lo:[0,1] neg_hi:[0,1]
	v_pk_add_f32 v[8:9], v[8:9], v[16:17] neg_lo:[0,1] neg_hi:[0,1]
	s_add_u32 s28, s28, 0x480
	s_addc_u32 s29, s29, 0
	s_cmp_lt_u32 s76, 32
	s_cbranch_scc0 .Lps_end
	s_lshl_b32 s50, s76, 3
	s_add_u32 s50, s50, 0x2000
	s_lshl_b32 s12, s50, 3
	s_add_u32 s20, s16, s12
	s_addc_u32 s21, s17, 0
	global_load_dwordx2 v[28:29], v23, s[20:21]
	s_lshl_b32 s12, s86, 5
	s_add_u32 s12, s12, s76
	s_mul_i32 s41, s12, 0x1e000
	s_add_u32 s22, s10, s41
	s_addc_u32 s23, s11, 0
	global_load_dwordx4 v[34:37], v21, s[22:23]
	s_add_u32 s22, s22, 0x2000
	s_addc_u32 s23, s23, 0
	global_load_dwordx4 v[38:41], v21, s[22:23]
	s_add_u32 s22, s22, 0x2000
	s_addc_u32 s23, s23, 0
	global_load_dwordx4 v[42:45], v21, s[22:23]
	s_add_u32 s22, s22, 0x2000
	s_addc_u32 s23, s23, 0
	global_load_dwordx4 v[46:49], v21, s[22:23]
	s_add_u32 s22, s22, 0x2000
	s_addc_u32 s23, s23, 0
	global_load_dwordx4 v[50:53], v21, s[22:23]
	s_add_u32 s22, s22, 0x2000
	s_addc_u32 s23, s23, 0
	global_load_dwordx4 v[54:57], v21, s[22:23]
	s_add_u32 s22, s22, 0x2000
	s_addc_u32 s23, s23, 0
	global_load_dwordx4 v[58:61], v21, s[22:23]
	s_add_u32 s22, s22, 0x2000
	s_addc_u32 s23, s23, 0
	global_load_dwordx4 v[62:65], v21, s[22:23]
	s_add_u32 s22, s22, 0x2000
	s_addc_u32 s23, s23, 0
	global_load_dwordx4 v[66:69], v21, s[22:23]
	s_add_u32 s22, s22, 0x2000
	s_addc_u32 s23, s23, 0
	global_load_dwordx4 v[70:73], v21, s[22:23]
	s_add_u32 s22, s22, 0x2000
	s_addc_u32 s23, s23, 0
	global_load_dwordx4 v[74:77], v21, s[22:23]
	s_add_u32 s22, s22, 0x2000
	s_addc_u32 s23, s23, 0
	global_load_dwordx4 v[78:81], v21, s[22:23]
	s_add_u32 s22, s22, 0x2000
	s_addc_u32 s23, s23, 0
	global_load_dwordx4 v[82:85], v21, s[22:23]
	s_add_u32 s22, s22, 0x2000
	s_addc_u32 s23, s23, 0
	global_load_dwordx4 v[86:89], v21, s[22:23]
	s_add_u32 s22, s22, 0x2000
	s_addc_u32 s23, s23, 0
	global_load_dwordx4 v[90:93], v21, s[22:23]
	s_mul_i32 s12, s50, 0x1080
	s_add_u32 s24, s14, s12
	s_addc_u32 s25, s15, 0
	global_load_dwordx2 v[94:95], v20, s[24:25]
	s_add_u32 s24, s24, 0x1080
	s_addc_u32 s25, s25, 0
	global_load_dwordx2 v[96:97], v20, s[24:25]
	s_add_u32 s24, s24, 0x1080
	s_addc_u32 s25, s25, 0
	global_load_dwordx2 v[98:99], v20, s[24:25]
	s_add_u32 s24, s24, 0x1080
	s_addc_u32 s25, s25, 0
	global_load_dwordx2 v[100:101], v20, s[24:25]
	s_add_u32 s24, s24, 0x1080
	s_addc_u32 s25, s25, 0
	global_load_dwordx2 v[102:103], v20, s[24:25]
	s_add_u32 s24, s24, 0x1080
	s_addc_u32 s25, s25, 0
	global_load_dwordx2 v[104:105], v20, s[24:25]
	s_add_u32 s24, s24, 0x1080
	s_addc_u32 s25, s25, 0
	global_load_dwordx2 v[106:107], v20, s[24:25]
	s_add_u32 s24, s24, 0x1080
	s_addc_u32 s25, s25, 0
	global_load_dwordx2 v[108:109], v20, s[24:25]
	s_mul_i32 s12, s50, 0x480
	s_add_u32 s28, s18, s12
	s_addc_u32 s29, s19, 0
	s_add_u32 s41, s41, 0x42f0000
	s_add_u32 s30, s8, s41
	s_addc_u32 s31, s9, 0
	s_waitcnt vmcnt(23)
	v_ffbh_u32_e32 v30, v29
	v_min_u32_e32 v30, 32, v30
	v_lshlrev_b64 v[28:29], v30, v[28:29]
	v_min_u32_e32 v28, 1, v28
	v_or_b32_e32 v28, v29, v28
	v_cvt_f32_u32_e32 v28, v28
	v_sub_u32_e32 v30, 32, v30
	v_ldexp_f32 v30, v28, v30
	v_mul_f32_e32 v30, 0x2f800000, v30
	v_fmamk_f32 v30, v30, 0x3a000000, v171
	v_mul_f32_e32 v28, 0x4f800000, v30
	v_cmp_gt_f32_e32 vcc, s51, v30
	s_nop 1
	v_cndmask_b32_e32 v30, v30, v28, vcc
	v_sqrt_f32_e32 v28, v30
	s_nop 0
	v_add_u32_e32 v29, -1, v28
	v_add_u32_e32 v31, 1, v28
	v_fma_f32 v32, -v29, v28, v30
	v_fma_f32 v33, -v31, v28, v30
	v_cmp_ge_f32_e64 s[34:35], 0, v32
	s_nop 1
	v_cndmask_b32_e64 v28, v28, v29, s[34:35]
	v_cmp_lt_f32_e64 s[34:35], 0, v33
	s_nop 1
	v_cndmask_b32_e64 v28, v28, v31, s[34:35]
	v_mul_f32_e32 v29, 0x37800000, v28
	v_cndmask_b32_e32 v28, v28, v29, vcc
	v_cmp_class_f32_e32 vcc, v30, v172
	s_nop 1
	v_cndmask_b32_e32 v30, v28, v30, vcc
	v_div_scale_f32 v28, s[34:35], v30, v30, 1.0
	v_rcp_f32_e32 v29, v28
	v_div_scale_f32 v31, vcc, 1.0, v30, 1.0
	v_fma_f32 v32, -v28, v29, 1.0
	v_fmac_f32_e32 v29, v32, v29
	v_mul_f32_e32 v32, v31, v29
	v_fma_f32 v33, -v28, v32, v31
	v_fmac_f32_e32 v32, v33, v29
	v_fma_f32 v28, -v28, v32, v31
	v_div_fmas_f32 v28, v28, v29, v32
	v_div_fixup_f32 v30, v28, v30, 1.0
	ds_write_b32 v24, v30
	s_waitcnt lgkmcnt(0)
	ds_read_b32 v146, v25 offset:0
	ds_read_b32 v147, v25 offset:4
	ds_read_b32 v148, v25 offset:8
	ds_read_b32 v149, v25 offset:12
	ds_read_b32 v150, v25 offset:16
	ds_read_b32 v151, v25 offset:20
	ds_read_b32 v152, v25 offset:24
	ds_read_b32 v153, v25 offset:28
	v_mov_b32_e32 v6, 0
	v_mov_b32_e32 v7, 0
	v_mov_b32_e32 v8, 0
	v_mov_b32_e32 v9, 0
	v_mov_b32_e32 v18, v27
	s_sub_u32 s36, 16, s1
	s_waitcnt vmcnt(0)
	s_waitcnt lgkmcnt(0)
	s_cmp_gt_u32 s36, 0
	s_cbranch_scc1 .Lps_i0
	v_pk_add_f32 v[6:7], v[6:7], v[34:35]
	v_pk_add_f32 v[8:9], v[8:9], v[36:37]
.Lps_i0:
	s_cmp_gt_u32 s36, 1
	s_cbranch_scc1 .Lps_i1
	v_pk_add_f32 v[6:7], v[6:7], v[38:39]
	v_pk_add_f32 v[8:9], v[8:9], v[40:41]
.Lps_i1:
	s_cmp_gt_u32 s36, 2
	s_cbranch_scc1 .Lps_i2
	v_pk_add_f32 v[6:7], v[6:7], v[42:43]
	v_pk_add_f32 v[8:9], v[8:9], v[44:45]
.Lps_i2:
	s_cmp_gt_u32 s36, 3
	s_cbranch_scc1 .Lps_i3
	v_pk_add_f32 v[6:7], v[6:7], v[46:47]
	v_pk_add_f32 v[8:9], v[8:9], v[48:49]
.Lps_i3:
	s_cmp_gt_u32 s36, 4
	s_cbranch_scc1 .Lps_i4
	v_pk_add_f32 v[6:7], v[6:7], v[50:51]
	v_pk_add_f32 v[8:9], v[8:9], v[52:53]
.Lps_i4:
	s_cmp_gt_u32 s36, 5
	s_cbranch_scc1 .Lps_i5
	v_pk_add_f32 v[6:7], v[6:7], v[54:55]
	v_pk_add_f32 v[8:9], v[8:9], v[56:57]
.Lps_i5:
	s_cmp_gt_u32 s36, 6
	s_cbranch_scc1 .Lps_i6
	v_pk_add_f32 v[6:7], v[6:7], v[58:59]
	v_pk_add_f32 v[8:9], v[8:9], v[60:61]
.Lps_i6:
	s_cmp_gt_u32 s36, 7
	s_cbranch_scc1 .Lps_i7
	v_pk_add_f32 v[6:7], v[6:7], v[62:63]
	v_pk_add_f32 v[8:9], v[8:9], v[64:65]
.Lps_i7:
	s_cmp_gt_u32 s36, 8
	s_cbranch_scc1 .Lps_i8
	v_pk_add_f32 v[6:7], v[6:7], v[66:67]
	v_pk_add_f32 v[8:9], v[8:9], v[68:69]
.Lps_i8:
	s_cmp_gt_u32 s36, 9
	s_cbranch_scc1 .Lps_i9
	v_pk_add_f32 v[6:7], v[6:7], v[70:71]
	v_pk_add_f32 v[8:9], v[8:9], v[72:73]
.Lps_i9:
	s_cmp_gt_u32 s36, 10
	s_cbranch_scc1 .Lps_i10
	v_pk_add_f32 v[6:7], v[6:7], v[74:75]
	v_pk_add_f32 v[8:9], v[8:9], v[76:77]
.Lps_i10:
	s_cmp_gt_u32 s36, 11
	s_cbranch_scc1 .Lps_i11
	v_pk_add_f32 v[6:7], v[6:7], v[78:79]
	v_pk_add_f32 v[8:9], v[8:9], v[80:81]
.Lps_i11:
	s_cmp_gt_u32 s36, 12
	s_cbranch_scc1 .Lps_i12
	v_pk_add_f32 v[6:7], v[6:7], v[82:83]
	v_pk_add_f32 v[8:9], v[8:9], v[84:85]
.Lps_i12:
	s_cmp_gt_u32 s36, 13
	s_cbranch_scc1 .Lps_i13
	v_pk_add_f32 v[6:7], v[6:7], v[86:87]
	v_pk_add_f32 v[8:9], v[8:9], v[88:89]
.Lps_i13:
	s_cmp_gt_u32 s36, 14
	s_cbranch_scc1 .Lps_i14
	v_pk_add_f32 v[6:7], v[6:7], v[90:91]
	v_pk_add_f32 v[8:9], v[8:9], v[92:93]
.Lps_i14:
	v_lshlrev_b32_e32 v110, 16, v94
	v_and_b32_e32 v111, 0xffff0000, v94
	v_lshlrev_b32_e32 v112, 16, v95
	v_and_b32_e32 v113, 0xffff0000, v95
	v_mul_f32_e32 v110, v146, v110
	v_mul_f32_e32 v111, v146, v111
	v_mul_f32_e32 v112, v146, v112
	v_mul_f32_e32 v113, v146, v113
	v_pk_mul_f32 v[110:111], v[2:3], v[110:111]
	v_pk_mul_f32 v[112:113], v[4:5], v[112:113]
	v_pk_add_f32 v[6:7], v[6:7], v[110:111]
	v_pk_add_f32 v[8:9], v[8:9], v[112:113]
	v_pk_fma_f32 v[14:15], v[6:7], v[18:19], v[110:111] op_sel_hi:[1,0,1] neg_lo:[0,0,1] neg_hi:[0,0,1]
	v_pk_fma_f32 v[16:17], v[8:9], v[18:19], v[112:113] op_sel_hi:[1,0,1] neg_lo:[0,0,1] neg_hi:[0,0,1]
	v_cvt_pk_bf16_f32 v14, v14, v15
	v_cvt_pk_bf16_f32 v15, v16, v17
	global_store_dwordx2 v22, v[14:15], s[28:29]
	s_add_u32 s28, s28, 0x480
	s_addc_u32 s29, s29, 0
	s_cmp_eq_u32 s1, 16
	s_cbranch_scc0 .Lps_l0_0
	v_pk_add_f32 v[6:7], v[6:7], v[34:35] neg_lo:[0,1] neg_hi:[0,1]
	v_pk_add_f32 v[8:9], v[8:9], v[36:37] neg_lo:[0,1] neg_hi:[0,1]
	s_branch .Lps_l0_x
.Lps_l0_0:
	s_cmp_eq_u32 s1, 8
	s_cbranch_scc0 .Lps_l0_1
	v_pk_add_f32 v[6:7], v[6:7], v[66:67] neg_lo:[0,1] neg_hi:[0,1]
	v_pk_add_f32 v[8:9], v[8:9], v[68:69] neg_lo:[0,1] neg_hi:[0,1]
	s_branch .Lps_l0_x
.Lps_l0_1:
	s_cmp_eq_u32 s1, 4
	s_cbranch_scc0 .Lps_l0_2
	v_pk_add_f32 v[6:7], v[6:7], v[82:83] neg_lo:[0,1] neg_hi:[0,1]
	v_pk_add_f32 v[8:9], v[8:9], v[84:85] neg_lo:[0,1] neg_hi:[0,1]
	s_branch .Lps_l0_x
.Lps_l0_2:
	s_cmp_eq_u32 s1, 2
	s_cbranch_scc0 .Lps_l0_3
	v_pk_add_f32 v[6:7], v[6:7], v[90:91] neg_lo:[0,1] neg_hi:[0,1]
	v_pk_add_f32 v[8:9], v[8:9], v[92:93] neg_lo:[0,1] neg_hi:[0,1]
	s_branch .Lps_l0_x
.Lps_l0_3:
.Lps_l0_x:
	v_lshlrev_b32_e32 v114, 16, v96
	v_and_b32_e32 v115, 0xffff0000, v96
	v_lshlrev_b32_e32 v116, 16, v97
	v_and_b32_e32 v117, 0xffff0000, v97
	v_mul_f32_e32 v114, v147, v114
	v_mul_f32_e32 v115, v147, v115
	v_mul_f32_e32 v116, v147, v116
	v_mul_f32_e32 v117, v147, v117
	v_pk_mul_f32 v[114:115], v[2:3], v[114:115]
	v_pk_mul_f32 v[116:117], v[4:5], v[116:117]
	v_pk_add_f32 v[6:7], v[6:7], v[114:115]
	v_pk_add_f32 v[8:9], v[8:9], v[116:117]
	v_pk_fma_f32 v[14:15], v[6:7], v[18:19], v[114:115] op_sel_hi:[1,0,1] neg_lo:[0,0,1] neg_hi:[0,0,1]
	v_pk_fma_f32 v[16:17], v[8:9], v[18:19], v[116:117] op_sel_hi:[1,0,1] neg_lo:[0,0,1] neg_hi:[0,0,1]
	v_cvt_pk_bf16_f32 v14, v14, v15
	v_cvt_pk_bf16_f32 v15, v16, v17
	global_store_dwordx2 v22, v[14:15], s[28:29]
	s_add_u32 s28, s28, 0x480
	s_addc_u32 s29, s29, 0
	s_cmp_eq_u32 s1, 16
	s_cbranch_scc0 .Lps_l1_0
	v_pk_add_f32 v[6:7], v[6:7], v[38:39] neg_lo:[0,1] neg_hi:[0,1]
	v_pk_add_f32 v[8:9], v[8:9], v[40:41] neg_lo:[0,1] neg_hi:[0,1]
	s_branch .Lps_l1_x
.Lps_l1_0:
	s_cmp_eq_u32 s1, 8
	s_cbranch_scc0 .Lps_l1_1
	v_pk_add_f32 v[6:7], v[6:7], v[70:71] neg_lo:[0,1] neg_hi:[0,1]
	v_pk_add_f32 v[8:9], v[8:9], v[72:73] neg_lo:[0,1] neg_hi:[0,1]
	s_branch .Lps_l1_x
.Lps_l1_1:
	s_cmp_eq_u32 s1, 4
	s_cbranch_scc0 .Lps_l1_2
	v_pk_add_f32 v[6:7], v[6:7], v[86:87] neg_lo:[0,1] neg_hi:[0,1]
	v_pk_add_f32 v[8:9], v[8:9], v[88:89] neg_lo:[0,1] neg_hi:[0,1]
	s_branch .Lps_l1_x
.Lps_l1_2:
	s_cmp_eq_u32 s1, 2
	s_cbranch_scc0 .Lps_l1_3
	v_pk_add_f32 v[6:7], v[6:7], v[110:111] neg_lo:[0,1] neg_hi:[0,1]
	v_pk_add_f32 v[8:9], v[8:9], v[112:113] neg_lo:[0,1] neg_hi:[0,1]
	s_branch .Lps_l1_x
.Lps_l1_3:
.Lps_l1_x:
	v_lshlrev_b32_e32 v118, 16, v98
	v_and_b32_e32 v119, 0xffff0000, v98
	v_lshlrev_b32_e32 v120, 16, v99
	v_and_b32_e32 v121, 0xffff0000, v99
	v_mul_f32_e32 v118, v148, v118
	v_mul_f32_e32 v119, v148, v119
	v_mul_f32_e32 v120, v148, v120
	v_mul_f32_e32 v121, v148, v121
	v_pk_mul_f32 v[118:119], v[2:3], v[118:119]
	v_pk_mul_f32 v[120:121], v[4:5], v[120:121]
	v_pk_add_f32 v[6:7], v[6:7], v[118:119]
	v_pk_add_f32 v[8:9], v[8:9], v[120:121]
	v_pk_fma_f32 v[14:15], v[6:7], v[18:19], v[118:119] op_sel_hi:[1,0,1] neg_lo:[0,0,1] neg_hi:[0,0,1]
	v_pk_fma_f32 v[16:17], v[8:9], v[18:19], v[120:121] op_sel_hi:[1,0,1] neg_lo:[0,0,1] neg_hi:[0,0,1]
	v_cvt_pk_bf16_f32 v14, v14, v15
	v_cvt_pk_bf16_f32 v15, v16, v17
	global_store_dwordx2 v22, v[14:15], s[28:29]
	s_add_u32 s28, s28, 0x480
	s_addc_u32 s29, s29, 0
	s_cmp_eq_u32 s1, 16
	s_cbranch_scc0 .Lps_l2_0
	v_pk_add_f32 v[6:7], v[6:7], v[42:43] neg_lo:[0,1] neg_hi:[0,1]
	v_pk_add_f32 v[8:9], v[8:9], v[44:45] neg_lo:[0,1] neg_hi:[0,1]
	s_branch .Lps_l2_x
.Lps_l2_0:
	s_cmp_eq_u32 s1, 8
	s_cbranch_scc0 .Lps_l2_1
	v_pk_add_f32 v[6:7], v[6:7], v[74:75] neg_lo:[0,1] neg_hi:[0,1]
	v_pk_add_f32 v[8:9], v[8:9], v[76:77] neg_lo:[0,1] neg_hi:[0,1]
	s_branch .Lps_l2_x
.Lps_l2_1:
	s_cmp_eq_u32 s1, 4
	s_cbranch_scc0 .Lps_l2_2
	v_pk_add_f32 v[6:7], v[6:7], v[90:91] neg_lo:[0,1] neg_hi:[0,1]
	v_pk_add_f32 v[8:9], v[8:9], v[92:93] neg_lo:[0,1] neg_hi:[0,1]
	s_branch .Lps_l2_x
.Lps_l2_2:
	s_cmp_eq_u32 s1, 2
	s_cbranch_scc0 .Lps_l2_3
	v_pk_add_f32 v[6:7], v[6:7], v[114:115] neg_lo:[0,1] neg_hi:[0,1]
	v_pk_add_f32 v[8:9], v[8:9], v[116:117] neg_lo:[0,1] neg_hi:[0,1]
	s_branch .Lps_l2_x
.Lps_l2_3:
.Lps_l2_x:
	v_lshlrev_b32_e32 v122, 16, v100
	v_and_b32_e32 v123, 0xffff0000, v100
	v_lshlrev_b32_e32 v124, 16, v101
	v_and_b32_e32 v125, 0xffff0000, v101
	v_mul_f32_e32 v122, v149, v122
	v_mul_f32_e32 v123, v149, v123
	v_mul_f32_e32 v124, v149, v124
	v_mul_f32_e32 v125, v149, v125
	v_pk_mul_f32 v[122:123], v[2:3], v[122:123]
	v_pk_mul_f32 v[124:125], v[4:5], v[124:125]
	v_pk_add_f32 v[6:7], v[6:7], v[122:123]
	v_pk_add_f32 v[8:9], v[8:9], v[124:125]
	v_pk_fma_f32 v[14:15], v[6:7], v[18:19], v[122:123] op_sel_hi:[1,0,1] neg_lo:[0,0,1] neg_hi:[0,0,1]
	v_pk_fma_f32 v[16:17], v[8:9], v[18:19], v[124:125] op_sel_hi:[1,0,1] neg_lo:[0,0,1] neg_hi:[0,0,1]
	v_cvt_pk_bf16_f32 v14, v14, v15
	v_cvt_pk_bf16_f32 v15, v16, v17
	global_store_dwordx2 v22, v[14:15], s[28:29]
	s_add_u32 s28, s28, 0x480
	s_addc_u32 s29, s29, 0
	s_cmp_eq_u32 s1, 16
	s_cbranch_scc0 .Lps_l3_0
	v_pk_add_f32 v[6:7], v[6:7], v[46:47] neg_lo:[0,1] neg_hi:[0,1]
	v_pk_add_f32 v[8:9], v[8:9], v[48:49] neg_lo:[0,1] neg_hi:[0,1]
	s_branch .Lps_l3_x
.Lps_l3_0:
	s_cmp_eq_u32 s1, 8
	s_cbranch_scc0 .Lps_l3_1
	v_pk_add_f32 v[6:7], v[6:7], v[78:79] neg_lo:[0,1] neg_hi:[0,1]
	v_pk_add_f32 v[8:9], v[8:9], v[80:81] neg_lo:[0,1] neg_hi:[0,1]
	s_branch .Lps_l3_x
.Lps_l3_1:
	s_cmp_eq_u32 s1, 4
	s_cbranch_scc0 .Lps_l3_2
	v_pk_add_f32 v[6:7], v[6:7], v[110:111] neg_lo:[0,1] neg_hi:[0,1]
	v_pk_add_f32 v[8:9], v[8:9], v[112:113] neg_lo:[0,1] neg_hi:[0,1]
	s_branch .Lps_l3_x
.Lps_l3_2:
	s_cmp_eq_u32 s1, 2
	s_cbranch_scc0 .Lps_l3_3
	v_pk_add_f32 v[6:7], v[6:7], v[118:119] neg_lo:[0,1] neg_hi:[0,1]
	v_pk_add_f32 v[8:9], v[8:9], v[120:121] neg_lo:[0,1] neg_hi:[0,1]
	s_branch .Lps_l3_x
.Lps_l3_3:
.Lps_l3_x:
	v_lshlrev_b32_e32 v126, 16, v102
	v_and_b32_e32 v127, 0xffff0000, v102
	v_lshlrev_b32_e32 v128, 16, v103
	v_and_b32_e32 v129, 0xffff0000, v103
	v_mul_f32_e32 v126, v150, v126
	v_mul_f32_e32 v127, v150, v127
	v_mul_f32_e32 v128, v150, v128
	v_mul_f32_e32 v129, v150, v129
	v_pk_mul_f32 v[126:127], v[2:3], v[126:127]
	v_pk_mul_f32 v[128:129], v[4:5], v[128:129]
	v_pk_add_f32 v[6:7], v[6:7], v[126:127]
	v_pk_add_f32 v[8:9], v[8:9], v[128:129]
	v_pk_fma_f32 v[14:15], v[6:7], v[18:19], v[126:127] op_sel_hi:[1,0,1] neg_lo:[0,0,1] neg_hi:[0,0,1]
	v_pk_fma_f32 v[16:17], v[8:9], v[18:19], v[128:129] op_sel_hi:[1,0,1] neg_lo:[0,0,1] neg_hi:[0,0,1]
	v_cvt_pk_bf16_f32 v14, v14, v15
	v_cvt_pk_bf16_f32 v15, v16, v17
	global_store_dwordx2 v22, v[14:15], s[28:29]
	s_add_u32 s28, s28, 0x480
	s_addc_u32 s29, s29, 0
	s_cmp_eq_u32 s1, 16
	s_cbranch_scc0 .Lps_l4_0
	v_pk_add_f32 v[6:7], v[6:7], v[50:51] neg_lo:[0,1] neg_hi:[0,1]
	v_pk_add_f32 v[8:9], v[8:9], v[52:53] neg_lo:[0,1] neg_hi:[0,1]
	s_branch .Lps_l4_x
.Lps_l4_0:
	s_cmp_eq_u32 s1, 8
	s_cbranch_scc0 .Lps_l4_1
	v_pk_add_f32 v[6:7], v[6:7], v[82:83] neg_lo:[0,1] neg_hi:[0,1]
	v_pk_add_f32 v[8:9], v[8:9], v[84:85] neg_lo:[0,1] neg_hi:[0,1]
	s_branch .Lps_l4_x
.Lps_l4_1:
	s_cmp_eq_u32 s1, 4
	s_cbranch_scc0 .Lps_l4_2
	v_pk_add_f32 v[6:7], v[6:7], v[114:115] neg_lo:[0,1] neg_hi:[0,1]
	v_pk_add_f32 v[8:9], v[8:9], v[116:117] neg_lo:[0,1] neg_hi:[0,1]
	s_branch .Lps_l4_x
.Lps_l4_2:
	s_cmp_eq_u32 s1, 2
	s_cbranch_scc0 .Lps_l4_3
	v_pk_add_f32 v[6:7], v[6:7], v[122:123] neg_lo:[0,1] neg_hi:[0,1]
	v_pk_add_f32 v[8:9], v[8:9], v[124:125] neg_lo:[0,1] neg_hi:[0,1]
	s_branch .Lps_l4_x
.Lps_l4_3:
.Lps_l4_x:
	v_lshlrev_b32_e32 v130, 16, v104
	v_and_b32_e32 v131, 0xffff0000, v104
	v_lshlrev_b32_e32 v132, 16, v105
	v_and_b32_e32 v133, 0xffff0000, v105
	v_mul_f32_e32 v130, v151, v130
	v_mul_f32_e32 v131, v151, v131
	v_mul_f32_e32 v132, v151, v132
	v_mul_f32_e32 v133, v151, v133
	v_pk_mul_f32 v[130:131], v[2:3], v[130:131]
	v_pk_mul_f32 v[132:133], v[4:5], v[132:133]
	v_pk_add_f32 v[6:7], v[6:7], v[130:131]
	v_pk_add_f32 v[8:9], v[8:9], v[132:133]
	v_pk_fma_f32 v[14:15], v[6:7], v[18:19], v[130:131] op_sel_hi:[1,0,1] neg_lo:[0,0,1] neg_hi:[0,0,1]
	v_pk_fma_f32 v[16:17], v[8:9], v[18:19], v[132:133] op_sel_hi:[1,0,1] neg_lo:[0,0,1] neg_hi:[0,0,1]
	v_cvt_pk_bf16_f32 v14, v14, v15
	v_cvt_pk_bf16_f32 v15, v16, v17
	global_store_dwordx2 v22, v[14:15], s[28:29]
	s_add_u32 s28, s28, 0x480
	s_addc_u32 s29, s29, 0
	s_cmp_eq_u32 s1, 16
	s_cbranch_scc0 .Lps_l5_0
	v_pk_add_f32 v[6:7], v[6:7], v[54:55] neg_lo:[0,1] neg_hi:[0,1]
	v_pk_add_f32 v[8:9], v[8:9], v[56:57] neg_lo:[0,1] neg_hi:[0,1]
	s_branch .Lps_l5_x
.Lps_l5_0:
	s_cmp_eq_u32 s1, 8
	s_cbranch_scc0 .Lps_l5_1
	v_pk_add_f32 v[6:7], v[6:7], v[86:87] neg_lo:[0,1] neg_hi:[0,1]
	v_pk_add_f32 v[8:9], v[8:9], v[88:89] neg_lo:[0,1] neg_hi:[0,1]
	s_branch .Lps_l5_x
.Lps_l5_1:
	s_cmp_eq_u32 s1, 4
	s_cbranch_scc0 .Lps_l5_2
	v_pk_add_f32 v[6:7], v[6:7], v[118:119] neg_lo:[0,1] neg_hi:[0,1]
	v_pk_add_f32 v[8:9], v[8:9], v[120:121] neg_lo:[0,1] neg_hi:[0,1]
	s_branch .Lps_l5_x
.Lps_l5_2:
	s_cmp_eq_u32 s1, 2
	s_cbranch_scc0 .Lps_l5_3
	v_pk_add_f32 v[6:7], v[6:7], v[126:127] neg_lo:[0,1] neg_hi:[0,1]
	v_pk_add_f32 v[8:9], v[8:9], v[128:129] neg_lo:[0,1] neg_hi:[0,1]
	s_branch .Lps_l5_x
.Lps_l5_3:
.Lps_l5_x:
	v_lshlrev_b32_e32 v134, 16, v106
	v_and_b32_e32 v135, 0xffff0000, v106
	v_lshlrev_b32_e32 v136, 16, v107
	v_and_b32_e32 v137, 0xffff0000, v107
	v_mul_f32_e32 v134, v152, v134
	v_mul_f32_e32 v135, v152, v135
	v_mul_f32_e32 v136, v152, v136
	v_mul_f32_e32 v137, v152, v137
	v_pk_mul_f32 v[134:135], v[2:3], v[134:135]
	v_pk_mul_f32 v[136:137], v[4:5], v[136:137]
	v_pk_add_f32 v[6:7], v[6:7], v[134:135]
	v_pk_add_f32 v[8:9], v[8:9], v[136:137]
	v_pk_fma_f32 v[14:15], v[6:7], v[18:19], v[134:135] op_sel_hi:[1,0,1] neg_lo:[0,0,1] neg_hi:[0,0,1]
	v_pk_fma_f32 v[16:17], v[8:9], v[18:19], v[136:137] op_sel_hi:[1,0,1] neg_lo:[0,0,1] neg_hi:[0,0,1]
	v_cvt_pk_bf16_f32 v14, v14, v15
	v_cvt_pk_bf16_f32 v15, v16, v17
	global_store_dwordx2 v22, v[14:15], s[28:29]
	s_add_u32 s28, s28, 0x480
	s_addc_u32 s29, s29, 0
	s_cmp_eq_u32 s1, 16
	s_cbranch_scc0 .Lps_l6_0
	v_pk_add_f32 v[6:7], v[6:7], v[58:59] neg_lo:[0,1] neg_hi:[0,1]
	v_pk_add_f32 v[8:9], v[8:9], v[60:61] neg_lo:[0,1] neg_hi:[0,1]
	s_branch .Lps_l6_x
.Lps_l6_0:
	s_cmp_eq_u32 s1, 8
	s_cbranch_scc0 .Lps_l6_1
	v_pk_add_f32 v[6:7], v[6:7], v[90:91] neg_lo:[0,1] neg_hi:[0,1]
	v_pk_add_f32 v[8:9], v[8:9], v[92:93] neg_lo:[0,1] neg_hi:[0,1]
	s_branch .Lps_l6_x
.Lps_l6_1:
	s_cmp_eq_u32 s1, 4
	s_cbranch_scc0 .Lps_l6_2
	v_pk_add_f32 v[6:7], v[6:7], v[122:123] neg_lo:[0,1] neg_hi:[0,1]
	v_pk_add_f32 v[8:9], v[8:9], v[124:125] neg_lo:[0,1] neg_hi:[0,1]
	s_branch .Lps_l6_x
.Lps_l6_2:
	s_cmp_eq_u32 s1, 2
	s_cbranch_scc0 .Lps_l6_3
	v_pk_add_f32 v[6:7], v[6:7], v[130:131] neg_lo:[0,1] neg_hi:[0,1]
	v_pk_add_f32 v[8:9], v[8:9], v[132:133] neg_lo:[0,1] neg_hi:[0,1]
	s_branch .Lps_l6_x
.Lps_l6_3:
.Lps_l6_x:
	v_lshlrev_b32_e32 v142, 16, v108
	v_and_b32_e32 v143, 0xffff0000, v108
	v_lshlrev_b32_e32 v144, 16, v109
	v_and_b32_e32 v145, 0xffff0000, v109
	v_mul_f32_e32 v142, v153, v142
	v_mul_f32_e32 v143, v153, v143
	v_mul_f32_e32 v144, v153, v144
	v_mul_f32_e32 v145, v153, v145
	v_pk_mul_f32 v[142:143], v[2:3], v[142:143]
	v_pk_mul_f32 v[144:145], v[4:5], v[144:145]
	v_pk_add_f32 v[6:7], v[6:7], v[142:143]
	v_pk_add_f32 v[8:9], v[8:9], v[144:145]
	v_pk_fma_f32 v[14:15], v[6:7], v[18:19], v[142:143] op_sel_hi:[1,0,1] neg_lo:[0,0,1] neg_hi:[0,0,1]
	v_pk_fma_f32 v[16:17], v[8:9], v[18:19], v[144:145] op_sel_hi:[1,0,1] neg_lo:[0,0,1] neg_hi:[0,0,1]
	v_cvt_pk_bf16_f32 v14, v14, v15
	v_cvt_pk_bf16_f32 v15, v16, v17
	global_store_dwordx2 v22, v[14:15], s[28:29]
	s_cmp_eq_u32 s1, 16
	s_cbranch_scc0 .Lps_l7_0
	v_pk_add_f32 v[6:7], v[6:7], v[62:63] neg_lo:[0,1] neg_hi:[0,1]
	v_pk_add_f32 v[8:9], v[8:9], v[64:65] neg_lo:[0,1] neg_hi:[0,1]
	s_branch .Lps_l7_x
.Lps_l7_0:
	s_cmp_eq_u32 s1, 8
	s_cbranch_scc0 .Lps_l7_1
	v_pk_add_f32 v[6:7], v[6:7], v[110:111] neg_lo:[0,1] neg_hi:[0,1]
	v_pk_add_f32 v[8:9], v[8:9], v[112:113] neg_lo:[0,1] neg_hi:[0,1]
	s_branch .Lps_l7_x
.Lps_l7_1:
	s_cmp_eq_u32 s1, 4
	s_cbranch_scc0 .Lps_l7_2
	v_pk_add_f32 v[6:7], v[6:7], v[126:127] neg_lo:[0,1] neg_hi:[0,1]
	v_pk_add_f32 v[8:9], v[8:9], v[128:129] neg_lo:[0,1] neg_hi:[0,1]
	s_branch .Lps_l7_x
.Lps_l7_2:
	s_cmp_eq_u32 s1, 2
	s_cbranch_scc0 .Lps_l7_3
	v_pk_add_f32 v[6:7], v[6:7], v[134:135] neg_lo:[0,1] neg_hi:[0,1]
	v_pk_add_f32 v[8:9], v[8:9], v[136:137] neg_lo:[0,1] neg_hi:[0,1]
	s_branch .Lps_l7_x
.Lps_l7_3:
.Lps_l7_x:
	global_store_dwordx4 v21, v[66:69], s[30:31]
	s_add_u32 s30, s30, 0x2000
	s_addc_u32 s31, s31, 0
	global_store_dwordx4 v21, v[70:73], s[30:31]
	s_add_u32 s30, s30, 0x2000
	s_addc_u32 s31, s31, 0
	global_store_dwordx4 v21, v[74:77], s[30:31]
	s_add_u32 s30, s30, 0x2000
	s_addc_u32 s31, s31, 0
	global_store_dwordx4 v21, v[78:81], s[30:31]
	s_add_u32 s30, s30, 0x2000
	s_addc_u32 s31, s31, 0
	global_store_dwordx4 v21, v[82:85], s[30:31]
	s_add_u32 s30, s30, 0x2000
	s_addc_u32 s31, s31, 0
	global_store_dwordx4 v21, v[86:89], s[30:31]
	s_add_u32 s30, s30, 0x2000
	s_addc_u32 s31, s31, 0
	global_store_dwordx4 v21, v[90:93], s[30:31]
	s_add_u32 s30, s30, 0x2000
	s_addc_u32 s31, s31, 0
	global_store_dwordx4 v21, v[110:113], s[30:31]
	s_add_u32 s30, s30, 0x2000
	s_addc_u32 s31, s31, 0
	global_store_dwordx4 v21, v[114:117], s[30:31]
	s_add_u32 s30, s30, 0x2000
	s_addc_u32 s31, s31, 0
	global_store_dwordx4 v21, v[118:121], s[30:31]
	s_add_u32 s30, s30, 0x2000
	s_addc_u32 s31, s31, 0
	global_store_dwordx4 v21, v[122:125], s[30:31]
	s_add_u32 s30, s30, 0x2000
	s_addc_u32 s31, s31, 0
	global_store_dwordx4 v21, v[126:129], s[30:31]
	s_add_u32 s30, s30, 0x2000
	s_addc_u32 s31, s31, 0
	global_store_dwordx4 v21, v[130:133], s[30:31]
	s_add_u32 s30, s30, 0x2000
	s_addc_u32 s31, s31, 0
	global_store_dwordx4 v21, v[134:137], s[30:31]
	s_add_u32 s30, s30, 0x2000
	s_addc_u32 s31, s31, 0
	global_store_dwordx4 v21, v[142:145], s[30:31]
.Lps_end:
	s_branch .LBB0_996

